# mods_units main loop: all 128 weight-row loads requested up front into free registers, FMA order unchanged (three inlined copies)
# baseline (speedup 1.0000x reference)
.LBB0_1025:
	s_ashr_i32 s7, s6, 8
	s_and_b32 s13, s6, 0xff
	s_mul_i32 s5, s7, 0x2400000
	s_mul_i32 s13, s13, 36
	s_mul_hi_i32 s4, s7, 0x2400000
	s_add_u32 s5, s8, s5
	s_addc_u32 s14, s9, s4
	s_lshl_b32 s80, s13, 2
	s_add_u32 s4, s5, s80
	s_addc_u32 s5, s14, 0
	v_lshl_add_u64 v[10:11], s[4:5], 0, v[0:1]
	global_load_dword v70, v[10:11], off nt
	s_mov_b64 s[98:99], 0x9000
	v_lshl_add_u64 v[12:13], v[10:11], 0, s[98:99]
	global_load_dword v71, v[12:13], off nt
	s_mov_b64 s[98:99], 0x12000
	v_lshl_add_u64 v[12:13], v[10:11], 0, s[98:99]
	global_load_dword v72, v[12:13], off nt
	s_mov_b64 s[98:99], 0x1b000
	v_lshl_add_u64 v[12:13], v[10:11], 0, s[98:99]
	global_load_dword v73, v[12:13], off nt
	s_mov_b64 s[98:99], 0x24000
	v_lshl_add_u64 v[12:13], v[10:11], 0, s[98:99]
	global_load_dword v74, v[12:13], off nt
	s_mov_b64 s[98:99], 0x2d000
	v_lshl_add_u64 v[12:13], v[10:11], 0, s[98:99]
	global_load_dword v75, v[12:13], off nt
	s_mov_b64 s[98:99], 0x36000
	v_lshl_add_u64 v[12:13], v[10:11], 0, s[98:99]
	global_load_dword v76, v[12:13], off nt
	s_mov_b64 s[98:99], 0x3f000
	v_lshl_add_u64 v[12:13], v[10:11], 0, s[98:99]
	global_load_dword v77, v[12:13], off nt
	s_mov_b64 s[98:99], 0x48000
	v_lshl_add_u64 v[12:13], v[10:11], 0, s[98:99]
	global_load_dword v78, v[12:13], off nt
	s_mov_b64 s[98:99], 0x51000
	v_lshl_add_u64 v[12:13], v[10:11], 0, s[98:99]
	global_load_dword v79, v[12:13], off nt
	s_mov_b64 s[98:99], 0x5a000
	v_lshl_add_u64 v[12:13], v[10:11], 0, s[98:99]
	global_load_dword v80, v[12:13], off nt
	s_mov_b64 s[98:99], 0x63000
	v_lshl_add_u64 v[12:13], v[10:11], 0, s[98:99]
	global_load_dword v81, v[12:13], off nt
	s_mov_b64 s[98:99], 0x6c000
	v_lshl_add_u64 v[12:13], v[10:11], 0, s[98:99]
	global_load_dword v82, v[12:13], off nt
	s_mov_b64 s[98:99], 0x75000
	v_lshl_add_u64 v[12:13], v[10:11], 0, s[98:99]
	global_load_dword v83, v[12:13], off nt
	s_mov_b64 s[98:99], 0x7e000
	v_lshl_add_u64 v[12:13], v[10:11], 0, s[98:99]
	global_load_dword v84, v[12:13], off nt
	s_mov_b64 s[98:99], 0x87000
	v_lshl_add_u64 v[12:13], v[10:11], 0, s[98:99]
	global_load_dword v85, v[12:13], off nt
	s_mov_b64 s[98:99], 0x90000
	v_lshl_add_u64 v[12:13], v[10:11], 0, s[98:99]
	global_load_dword v86, v[12:13], off nt
	s_mov_b64 s[98:99], 0x99000
	v_lshl_add_u64 v[12:13], v[10:11], 0, s[98:99]
	global_load_dword v87, v[12:13], off nt
	s_mov_b64 s[98:99], 0xa2000
	v_lshl_add_u64 v[12:13], v[10:11], 0, s[98:99]
	global_load_dword v88, v[12:13], off nt
	s_mov_b64 s[98:99], 0xab000
	v_lshl_add_u64 v[12:13], v[10:11], 0, s[98:99]
	global_load_dword v89, v[12:13], off nt
	s_mov_b64 s[98:99], 0xb4000
	v_lshl_add_u64 v[12:13], v[10:11], 0, s[98:99]
	global_load_dword v90, v[12:13], off nt
	s_mov_b64 s[98:99], 0xbd000
	v_lshl_add_u64 v[12:13], v[10:11], 0, s[98:99]
	global_load_dword v91, v[12:13], off nt
	s_mov_b64 s[98:99], 0xc6000
	v_lshl_add_u64 v[12:13], v[10:11], 0, s[98:99]
	global_load_dword v92, v[12:13], off nt
	s_mov_b64 s[98:99], 0xcf000
	v_lshl_add_u64 v[12:13], v[10:11], 0, s[98:99]
	global_load_dword v93, v[12:13], off nt
	s_mov_b64 s[98:99], 0xd8000
	v_lshl_add_u64 v[12:13], v[10:11], 0, s[98:99]
	global_load_dword v94, v[12:13], off nt
	s_mov_b64 s[98:99], 0xe1000
	v_lshl_add_u64 v[12:13], v[10:11], 0, s[98:99]
	global_load_dword v95, v[12:13], off nt
	s_mov_b64 s[98:99], 0xea000
	v_lshl_add_u64 v[12:13], v[10:11], 0, s[98:99]
	global_load_dword v96, v[12:13], off nt
	s_mov_b64 s[98:99], 0xf3000
	v_lshl_add_u64 v[12:13], v[10:11], 0, s[98:99]
	global_load_dword v97, v[12:13], off nt
	s_mov_b64 s[98:99], 0xfc000
	v_lshl_add_u64 v[12:13], v[10:11], 0, s[98:99]
	global_load_dword v98, v[12:13], off nt
	s_mov_b64 s[98:99], 0x105000
	v_lshl_add_u64 v[12:13], v[10:11], 0, s[98:99]
	global_load_dword v99, v[12:13], off nt
	s_mov_b64 s[98:99], 0x10e000
	v_lshl_add_u64 v[12:13], v[10:11], 0, s[98:99]
	global_load_dword v100, v[12:13], off nt
	s_mov_b64 s[98:99], 0x117000
	v_lshl_add_u64 v[12:13], v[10:11], 0, s[98:99]
	global_load_dword v101, v[12:13], off nt
	s_mov_b64 s[98:99], 0x120000
	v_lshl_add_u64 v[12:13], v[10:11], 0, s[98:99]
	global_load_dword v102, v[12:13], off nt
	s_mov_b64 s[98:99], 0x129000
	v_lshl_add_u64 v[12:13], v[10:11], 0, s[98:99]
	global_load_dword v103, v[12:13], off nt
	s_mov_b64 s[98:99], 0x132000
	v_lshl_add_u64 v[12:13], v[10:11], 0, s[98:99]
	global_load_dword v104, v[12:13], off nt
	s_mov_b64 s[98:99], 0x13b000
	v_lshl_add_u64 v[12:13], v[10:11], 0, s[98:99]
	global_load_dword v105, v[12:13], off nt
	s_mov_b64 s[98:99], 0x144000
	v_lshl_add_u64 v[12:13], v[10:11], 0, s[98:99]
	global_load_dword v106, v[12:13], off nt
	s_mov_b64 s[98:99], 0x14d000
	v_lshl_add_u64 v[12:13], v[10:11], 0, s[98:99]
	global_load_dword v107, v[12:13], off nt
	s_mov_b64 s[98:99], 0x156000
	v_lshl_add_u64 v[12:13], v[10:11], 0, s[98:99]
	global_load_dword v108, v[12:13], off nt
	s_mov_b64 s[98:99], 0x15f000
	v_lshl_add_u64 v[12:13], v[10:11], 0, s[98:99]
	global_load_dword v109, v[12:13], off nt
	s_mov_b64 s[98:99], 0x168000
	v_lshl_add_u64 v[12:13], v[10:11], 0, s[98:99]
	global_load_dword v110, v[12:13], off nt
	s_mov_b64 s[98:99], 0x171000
	v_lshl_add_u64 v[12:13], v[10:11], 0, s[98:99]
	global_load_dword v111, v[12:13], off nt
	s_mov_b64 s[98:99], 0x17a000
	v_lshl_add_u64 v[12:13], v[10:11], 0, s[98:99]
	global_load_dword v112, v[12:13], off nt
	s_mov_b64 s[98:99], 0x183000
	v_lshl_add_u64 v[12:13], v[10:11], 0, s[98:99]
	global_load_dword v113, v[12:13], off nt
	s_mov_b64 s[98:99], 0x18c000
	v_lshl_add_u64 v[12:13], v[10:11], 0, s[98:99]
	global_load_dword v114, v[12:13], off nt
	s_mov_b64 s[98:99], 0x195000
	v_lshl_add_u64 v[12:13], v[10:11], 0, s[98:99]
	global_load_dword v115, v[12:13], off nt
	s_mov_b64 s[98:99], 0x19e000
	v_lshl_add_u64 v[12:13], v[10:11], 0, s[98:99]
	global_load_dword v116, v[12:13], off nt
	s_mov_b64 s[98:99], 0x1a7000
	v_lshl_add_u64 v[12:13], v[10:11], 0, s[98:99]
	global_load_dword v117, v[12:13], off nt
	s_mov_b64 s[98:99], 0x1b0000
	v_lshl_add_u64 v[12:13], v[10:11], 0, s[98:99]
	global_load_dword v118, v[12:13], off nt
	s_mov_b64 s[98:99], 0x1b9000
	v_lshl_add_u64 v[12:13], v[10:11], 0, s[98:99]
	global_load_dword v119, v[12:13], off nt
	s_mov_b64 s[98:99], 0x1c2000
	v_lshl_add_u64 v[12:13], v[10:11], 0, s[98:99]
	global_load_dword v120, v[12:13], off nt
	s_mov_b64 s[98:99], 0x1cb000
	v_lshl_add_u64 v[12:13], v[10:11], 0, s[98:99]
	global_load_dword v121, v[12:13], off nt
	s_mov_b64 s[98:99], 0x1d4000
	v_lshl_add_u64 v[12:13], v[10:11], 0, s[98:99]
	global_load_dword v122, v[12:13], off nt
	s_mov_b64 s[98:99], 0x1dd000
	v_lshl_add_u64 v[12:13], v[10:11], 0, s[98:99]
	global_load_dword v123, v[12:13], off nt
	s_mov_b64 s[98:99], 0x1e6000
	v_lshl_add_u64 v[12:13], v[10:11], 0, s[98:99]
	global_load_dword v124, v[12:13], off nt
	s_mov_b64 s[98:99], 0x1ef000
	v_lshl_add_u64 v[12:13], v[10:11], 0, s[98:99]
	global_load_dword v125, v[12:13], off nt
	s_mov_b64 s[98:99], 0x1f8000
	v_lshl_add_u64 v[12:13], v[10:11], 0, s[98:99]
	global_load_dword v126, v[12:13], off nt
	s_mov_b64 s[98:99], 0x201000
	v_lshl_add_u64 v[12:13], v[10:11], 0, s[98:99]
	global_load_dword v127, v[12:13], off nt
	s_mov_b64 s[98:99], 0x20a000
	v_lshl_add_u64 v[12:13], v[10:11], 0, s[98:99]
	global_load_dword v128, v[12:13], off nt
	s_mov_b64 s[98:99], 0x213000
	v_lshl_add_u64 v[12:13], v[10:11], 0, s[98:99]
	global_load_dword v129, v[12:13], off nt
	s_mov_b64 s[98:99], 0x21c000
	v_lshl_add_u64 v[12:13], v[10:11], 0, s[98:99]
	global_load_dword v130, v[12:13], off nt
	s_mov_b64 s[98:99], 0x225000
	v_lshl_add_u64 v[12:13], v[10:11], 0, s[98:99]
	global_load_dword v131, v[12:13], off nt
	s_mov_b64 s[98:99], 0x22e000
	v_lshl_add_u64 v[12:13], v[10:11], 0, s[98:99]
	global_load_dword v132, v[12:13], off nt
	s_mov_b64 s[98:99], 0x237000
	v_lshl_add_u64 v[12:13], v[10:11], 0, s[98:99]
	global_load_dword v133, v[12:13], off nt
	s_mov_b64 s[98:99], 0x240000
	v_lshl_add_u64 v[12:13], v[10:11], 0, s[98:99]
	global_load_dword v134, v[12:13], off nt
	s_mov_b64 s[98:99], 0x249000
	v_lshl_add_u64 v[12:13], v[10:11], 0, s[98:99]
	global_load_dword v135, v[12:13], off nt
	s_mov_b64 s[98:99], 0x252000
	v_lshl_add_u64 v[12:13], v[10:11], 0, s[98:99]
	global_load_dword v136, v[12:13], off nt
	s_mov_b64 s[98:99], 0x25b000
	v_lshl_add_u64 v[12:13], v[10:11], 0, s[98:99]
	global_load_dword v137, v[12:13], off nt
	s_mov_b64 s[98:99], 0x264000
	v_lshl_add_u64 v[12:13], v[10:11], 0, s[98:99]
	global_load_dword v138, v[12:13], off nt
	s_mov_b64 s[98:99], 0x26d000
	v_lshl_add_u64 v[12:13], v[10:11], 0, s[98:99]
	global_load_dword v139, v[12:13], off nt
	s_mov_b64 s[98:99], 0x276000
	v_lshl_add_u64 v[12:13], v[10:11], 0, s[98:99]
	global_load_dword v140, v[12:13], off nt
	s_mov_b64 s[98:99], 0x27f000
	v_lshl_add_u64 v[12:13], v[10:11], 0, s[98:99]
	global_load_dword v141, v[12:13], off nt
	s_mov_b64 s[98:99], 0x288000
	v_lshl_add_u64 v[12:13], v[10:11], 0, s[98:99]
	global_load_dword v142, v[12:13], off nt
	s_mov_b64 s[98:99], 0x291000
	v_lshl_add_u64 v[12:13], v[10:11], 0, s[98:99]
	global_load_dword v143, v[12:13], off nt
	s_mov_b64 s[98:99], 0x29a000
	v_lshl_add_u64 v[12:13], v[10:11], 0, s[98:99]
	global_load_dword v144, v[12:13], off nt
	s_mov_b64 s[98:99], 0x2a3000
	v_lshl_add_u64 v[12:13], v[10:11], 0, s[98:99]
	global_load_dword v145, v[12:13], off nt
	s_mov_b64 s[98:99], 0x2ac000
	v_lshl_add_u64 v[12:13], v[10:11], 0, s[98:99]
	global_load_dword v146, v[12:13], off nt
	s_mov_b64 s[98:99], 0x2b5000
	v_lshl_add_u64 v[12:13], v[10:11], 0, s[98:99]
	global_load_dword v147, v[12:13], off nt
	s_mov_b64 s[98:99], 0x2be000
	v_lshl_add_u64 v[12:13], v[10:11], 0, s[98:99]
	global_load_dword v148, v[12:13], off nt
	s_mov_b64 s[98:99], 0x2c7000
	v_lshl_add_u64 v[12:13], v[10:11], 0, s[98:99]
	global_load_dword v149, v[12:13], off nt
	s_mov_b64 s[98:99], 0x2d0000
	v_lshl_add_u64 v[12:13], v[10:11], 0, s[98:99]
	global_load_dword v150, v[12:13], off nt
	s_mov_b64 s[98:99], 0x2d9000
	v_lshl_add_u64 v[12:13], v[10:11], 0, s[98:99]
	global_load_dword v151, v[12:13], off nt
	s_mov_b64 s[98:99], 0x2e2000
	v_lshl_add_u64 v[12:13], v[10:11], 0, s[98:99]
	global_load_dword v152, v[12:13], off nt
	s_mov_b64 s[98:99], 0x2eb000
	v_lshl_add_u64 v[12:13], v[10:11], 0, s[98:99]
	global_load_dword v153, v[12:13], off nt
	s_mov_b64 s[98:99], 0x2f4000
	v_lshl_add_u64 v[12:13], v[10:11], 0, s[98:99]
	global_load_dword v154, v[12:13], off nt
	s_mov_b64 s[98:99], 0x2fd000
	v_lshl_add_u64 v[12:13], v[10:11], 0, s[98:99]
	global_load_dword v155, v[12:13], off nt
	s_mov_b64 s[98:99], 0x306000
	v_lshl_add_u64 v[12:13], v[10:11], 0, s[98:99]
	global_load_dword v156, v[12:13], off nt
	s_mov_b64 s[98:99], 0x30f000
	v_lshl_add_u64 v[12:13], v[10:11], 0, s[98:99]
	global_load_dword v157, v[12:13], off nt
	s_mov_b64 s[98:99], 0x318000
	v_lshl_add_u64 v[12:13], v[10:11], 0, s[98:99]
	global_load_dword v158, v[12:13], off nt
	s_mov_b64 s[98:99], 0x321000
	v_lshl_add_u64 v[12:13], v[10:11], 0, s[98:99]
	global_load_dword v159, v[12:13], off nt
	s_mov_b64 s[98:99], 0x32a000
	v_lshl_add_u64 v[12:13], v[10:11], 0, s[98:99]
	global_load_dword v160, v[12:13], off nt
	s_mov_b64 s[98:99], 0x333000
	v_lshl_add_u64 v[12:13], v[10:11], 0, s[98:99]
	global_load_dword v161, v[12:13], off nt
	s_mov_b64 s[98:99], 0x33c000
	v_lshl_add_u64 v[12:13], v[10:11], 0, s[98:99]
	global_load_dword v162, v[12:13], off nt
	s_mov_b64 s[98:99], 0x345000
	v_lshl_add_u64 v[12:13], v[10:11], 0, s[98:99]
	global_load_dword v163, v[12:13], off nt
	s_mov_b64 s[98:99], 0x34e000
	v_lshl_add_u64 v[12:13], v[10:11], 0, s[98:99]
	global_load_dword v164, v[12:13], off nt
	s_mov_b64 s[98:99], 0x357000
	v_lshl_add_u64 v[12:13], v[10:11], 0, s[98:99]
	global_load_dword v165, v[12:13], off nt
	s_mov_b64 s[98:99], 0x360000
	v_lshl_add_u64 v[12:13], v[10:11], 0, s[98:99]
	global_load_dword v166, v[12:13], off nt
	s_mov_b64 s[98:99], 0x369000
	v_lshl_add_u64 v[12:13], v[10:11], 0, s[98:99]
	global_load_dword v167, v[12:13], off nt
	s_mov_b64 s[98:99], 0x372000
	v_lshl_add_u64 v[12:13], v[10:11], 0, s[98:99]
	global_load_dword v168, v[12:13], off nt
	s_mov_b64 s[98:99], 0x37b000
	v_lshl_add_u64 v[12:13], v[10:11], 0, s[98:99]
	global_load_dword v169, v[12:13], off nt
	s_mov_b64 s[98:99], 0x384000
	v_lshl_add_u64 v[12:13], v[10:11], 0, s[98:99]
	global_load_dword v170, v[12:13], off nt
	s_mov_b64 s[98:99], 0x38d000
	v_lshl_add_u64 v[12:13], v[10:11], 0, s[98:99]
	global_load_dword v171, v[12:13], off nt
	s_mov_b64 s[98:99], 0x396000
	v_lshl_add_u64 v[12:13], v[10:11], 0, s[98:99]
	global_load_dword v172, v[12:13], off nt
	s_mov_b64 s[98:99], 0x39f000
	v_lshl_add_u64 v[12:13], v[10:11], 0, s[98:99]
	global_load_dword v173, v[12:13], off nt
	s_mov_b64 s[98:99], 0x3a8000
	v_lshl_add_u64 v[12:13], v[10:11], 0, s[98:99]
	global_load_dword v174, v[12:13], off nt
	s_mov_b64 s[98:99], 0x3b1000
	v_lshl_add_u64 v[12:13], v[10:11], 0, s[98:99]
	global_load_dword v175, v[12:13], off nt
	s_mov_b64 s[98:99], 0x3ba000
	v_lshl_add_u64 v[12:13], v[10:11], 0, s[98:99]
	global_load_dword v176, v[12:13], off nt
	s_mov_b64 s[98:99], 0x3c3000
	v_lshl_add_u64 v[12:13], v[10:11], 0, s[98:99]
	global_load_dword v177, v[12:13], off nt
	s_mov_b64 s[98:99], 0x3cc000
	v_lshl_add_u64 v[12:13], v[10:11], 0, s[98:99]
	global_load_dword v178, v[12:13], off nt
	s_mov_b64 s[98:99], 0x3d5000
	v_lshl_add_u64 v[12:13], v[10:11], 0, s[98:99]
	global_load_dword v179, v[12:13], off nt
	s_mov_b64 s[98:99], 0x3de000
	v_lshl_add_u64 v[12:13], v[10:11], 0, s[98:99]
	global_load_dword v180, v[12:13], off nt
	s_mov_b64 s[98:99], 0x3e7000
	v_lshl_add_u64 v[12:13], v[10:11], 0, s[98:99]
	global_load_dword v181, v[12:13], off nt
	s_mov_b64 s[98:99], 0x3f0000
	v_lshl_add_u64 v[12:13], v[10:11], 0, s[98:99]
	global_load_dword v182, v[12:13], off nt
	s_mov_b64 s[98:99], 0x3f9000
	v_lshl_add_u64 v[12:13], v[10:11], 0, s[98:99]
	global_load_dword v183, v[12:13], off nt
	s_mov_b64 s[98:99], 0x402000
	v_lshl_add_u64 v[12:13], v[10:11], 0, s[98:99]
	global_load_dword v184, v[12:13], off nt
	s_mov_b64 s[98:99], 0x40b000
	v_lshl_add_u64 v[12:13], v[10:11], 0, s[98:99]
	global_load_dword v185, v[12:13], off nt
	s_mov_b64 s[98:99], 0x414000
	v_lshl_add_u64 v[12:13], v[10:11], 0, s[98:99]
	global_load_dword v186, v[12:13], off nt
	s_mov_b64 s[98:99], 0x41d000
	v_lshl_add_u64 v[12:13], v[10:11], 0, s[98:99]
	global_load_dword v187, v[12:13], off nt
	s_mov_b64 s[98:99], 0x426000
	v_lshl_add_u64 v[12:13], v[10:11], 0, s[98:99]
	global_load_dword v188, v[12:13], off nt
	s_mov_b64 s[98:99], 0x42f000
	v_lshl_add_u64 v[12:13], v[10:11], 0, s[98:99]
	global_load_dword v189, v[12:13], off nt
	s_mov_b64 s[98:99], 0x438000
	v_lshl_add_u64 v[12:13], v[10:11], 0, s[98:99]
	global_load_dword v190, v[12:13], off nt
	s_mov_b64 s[98:99], 0x441000
	v_lshl_add_u64 v[12:13], v[10:11], 0, s[98:99]
	global_load_dword v191, v[12:13], off nt
	s_mov_b64 s[98:99], 0x44a000
	v_lshl_add_u64 v[12:13], v[10:11], 0, s[98:99]
	global_load_dword v192, v[12:13], off nt
	s_mov_b64 s[98:99], 0x453000
	v_lshl_add_u64 v[12:13], v[10:11], 0, s[98:99]
	global_load_dword v193, v[12:13], off nt
	s_mov_b64 s[98:99], 0x45c000
	v_lshl_add_u64 v[12:13], v[10:11], 0, s[98:99]
	global_load_dword v194, v[12:13], off nt
	s_mov_b64 s[98:99], 0x465000
	v_lshl_add_u64 v[12:13], v[10:11], 0, s[98:99]
	global_load_dword v195, v[12:13], off nt
	s_mov_b64 s[98:99], 0x46e000
	v_lshl_add_u64 v[12:13], v[10:11], 0, s[98:99]
	global_load_dword v196, v[12:13], off nt
	s_mov_b64 s[98:99], 0x477000
	v_lshl_add_u64 v[12:13], v[10:11], 0, s[98:99]
	global_load_dword v197, v[12:13], off nt
	v_mov_b32_e32 v13, s12
	ds_read_b128 v[14:17], v13
	ds_read_b128 v[18:21], v13 offset:16
	ds_read_b128 v[22:25], v13 offset:32
	ds_read_b128 v[26:29], v13 offset:48
	ds_read_b128 v[30:33], v13 offset:4096
	s_waitcnt lgkmcnt(4)
	s_waitcnt vmcnt(63)
	v_fma_f32 v7, v70, v14, 0
	v_fmac_f32_e32 v7, v71, v15
	v_fmac_f32_e32 v7, v72, v16
	v_fmac_f32_e32 v7, v73, v17
	ds_read_b128 v[14:17], v13 offset:4112
	s_waitcnt lgkmcnt(1)
	v_fma_f32 v9, v70, v30, 0
	v_fmac_f32_e32 v9, v71, v31
	v_fmac_f32_e32 v9, v72, v32
	v_fmac_f32_e32 v9, v73, v33
	s_waitcnt lgkmcnt(0)
	v_fmac_f32_e32 v9, v74, v14
	v_fmac_f32_e32 v9, v75, v15
	ds_read_b128 v[34:37], v13 offset:8192
	v_fmac_f32_e32 v9, v76, v16
	v_fmac_f32_e32 v9, v77, v17
	ds_read_b128 v[14:17], v13 offset:4128
	ds_read_b128 v[30:33], v13 offset:8208
	s_waitcnt lgkmcnt(2)
	v_fma_f32 v12, v70, v34, 0
	v_fmac_f32_e32 v7, v74, v18
	v_fmac_f32_e32 v12, v71, v35
	v_fmac_f32_e32 v7, v75, v19
	s_waitcnt lgkmcnt(1)
	v_fmac_f32_e32 v9, v78, v14
	v_fmac_f32_e32 v12, v72, v36
	v_fmac_f32_e32 v7, v76, v20
	v_fmac_f32_e32 v9, v79, v15
	v_fmac_f32_e32 v12, v73, v37
	v_fmac_f32_e32 v7, v77, v21
	ds_read_b128 v[18:21], v13 offset:8224
	v_fmac_f32_e32 v9, v80, v16
	v_fmac_f32_e32 v9, v81, v17
	ds_read_b128 v[14:17], v13 offset:4144
	s_waitcnt lgkmcnt(2)
	v_fmac_f32_e32 v12, v74, v30
	v_fmac_f32_e32 v12, v75, v31
	v_fmac_f32_e32 v7, v78, v22
	v_fmac_f32_e32 v12, v76, v32
	v_fmac_f32_e32 v7, v79, v23
	v_fmac_f32_e32 v12, v77, v33
	v_fmac_f32_e32 v7, v80, v24
	v_fmac_f32_e32 v7, v81, v25
	ds_read_b128 v[22:25], v13 offset:8256
	s_waitcnt lgkmcnt(2)
	v_fmac_f32_e32 v12, v78, v18
	v_fmac_f32_e32 v12, v79, v19
	v_fmac_f32_e32 v12, v80, v20
	v_fmac_f32_e32 v12, v81, v21
	s_waitcnt lgkmcnt(1)
	v_fmac_f32_e32 v9, v82, v14
	ds_read_b128 v[18:21], v13 offset:8240
	v_fmac_f32_e32 v9, v83, v15
	v_fmac_f32_e32 v9, v84, v16
	v_fmac_f32_e32 v9, v85, v17
	ds_read_b128 v[14:17], v13 offset:64
	v_fmac_f32_e32 v7, v82, v26
	s_waitcnt lgkmcnt(1)
	v_fmac_f32_e32 v12, v82, v18
	v_fmac_f32_e32 v7, v83, v27
	v_fmac_f32_e32 v12, v83, v19
	v_fmac_f32_e32 v7, v84, v28
	v_fmac_f32_e32 v12, v84, v20
	v_fmac_f32_e32 v7, v85, v29
	v_fmac_f32_e32 v12, v85, v21
	ds_read_b128 v[18:21], v13 offset:4160
	s_waitcnt lgkmcnt(1)
	v_fmac_f32_e32 v7, v86, v14
	v_fmac_f32_e32 v7, v87, v15
	v_fmac_f32_e32 v7, v88, v16
	v_fmac_f32_e32 v7, v89, v17
	ds_read_b128 v[14:17], v13 offset:80
	s_waitcnt lgkmcnt(1)
	v_fmac_f32_e32 v9, v86, v18
	v_fmac_f32_e32 v9, v87, v19
	v_fmac_f32_e32 v9, v88, v20
	v_fmac_f32_e32 v9, v89, v21
	ds_read_b128 v[18:21], v13 offset:4176
	s_waitcnt lgkmcnt(1)
	v_fmac_f32_e32 v7, v90, v14
	v_fmac_f32_e32 v7, v91, v15
	v_fmac_f32_e32 v7, v92, v16
	v_fmac_f32_e32 v7, v93, v17
	ds_read_b128 v[14:17], v13 offset:96
	s_waitcnt lgkmcnt(1)
	v_fmac_f32_e32 v9, v90, v18
	v_fmac_f32_e32 v9, v91, v19
	v_fmac_f32_e32 v9, v92, v20
	v_fmac_f32_e32 v9, v93, v21
	ds_read_b128 v[18:21], v13 offset:4192
	s_waitcnt lgkmcnt(1)
	v_fmac_f32_e32 v7, v94, v14
	v_fmac_f32_e32 v7, v95, v15
	v_fmac_f32_e32 v7, v96, v16
	v_fmac_f32_e32 v7, v97, v17
	ds_read_b128 v[14:17], v13 offset:112
	s_waitcnt lgkmcnt(1)
	v_fmac_f32_e32 v9, v94, v18
	v_fmac_f32_e32 v9, v95, v19
	v_fmac_f32_e32 v9, v96, v20
	v_fmac_f32_e32 v9, v97, v21
	ds_read_b128 v[18:21], v13 offset:4208
	s_waitcnt lgkmcnt(1)
	v_fmac_f32_e32 v7, v98, v14
	v_fmac_f32_e32 v7, v99, v15
	v_fmac_f32_e32 v12, v86, v22
	v_fmac_f32_e32 v12, v87, v23
	s_nop 0
	v_fmac_f32_e32 v12, v88, v24
	v_fmac_f32_e32 v7, v100, v16
	v_fmac_f32_e32 v12, v89, v25
	v_fmac_f32_e32 v7, v101, v17
	ds_read_b128 v[14:17], v13 offset:128
	s_waitcnt lgkmcnt(1)
	v_fmac_f32_e32 v9, v98, v18
	v_fmac_f32_e32 v9, v99, v19
	v_fmac_f32_e32 v9, v100, v20
	v_fmac_f32_e32 v9, v101, v21
	ds_read_b128 v[18:21], v13 offset:4224
	s_waitcnt lgkmcnt(1)
	v_fmac_f32_e32 v7, v102, v14
	v_fmac_f32_e32 v7, v103, v15
	v_fmac_f32_e32 v7, v104, v16
	v_fmac_f32_e32 v7, v105, v17
	ds_read_b128 v[14:17], v13 offset:144
	s_waitcnt lgkmcnt(1)
	v_fmac_f32_e32 v9, v102, v18
	v_fmac_f32_e32 v9, v103, v19
	v_fmac_f32_e32 v9, v104, v20
	v_fmac_f32_e32 v9, v105, v21
	ds_read_b128 v[18:21], v13 offset:4240
	s_waitcnt lgkmcnt(1)
	v_fmac_f32_e32 v7, v106, v14
	v_fmac_f32_e32 v7, v107, v15
	v_fmac_f32_e32 v7, v108, v16
	v_fmac_f32_e32 v7, v109, v17
	ds_read_b128 v[14:17], v13 offset:160
	s_waitcnt lgkmcnt(1)
	v_fmac_f32_e32 v9, v106, v18
	v_fmac_f32_e32 v9, v107, v19
	v_fmac_f32_e32 v9, v108, v20
	v_fmac_f32_e32 v9, v109, v21
	ds_read_b128 v[18:21], v13 offset:4256
	s_waitcnt lgkmcnt(1)
	v_fmac_f32_e32 v7, v110, v14
	v_fmac_f32_e32 v7, v111, v15
	v_fmac_f32_e32 v7, v112, v16
	v_fmac_f32_e32 v7, v113, v17
	ds_read_b128 v[14:17], v13 offset:176
	s_waitcnt lgkmcnt(1)
	v_fmac_f32_e32 v9, v110, v18
	v_fmac_f32_e32 v9, v111, v19
	v_fmac_f32_e32 v9, v112, v20
	v_fmac_f32_e32 v9, v113, v21
	ds_read_b128 v[18:21], v13 offset:4272
	s_waitcnt lgkmcnt(1)
	v_fmac_f32_e32 v7, v114, v14
	v_fmac_f32_e32 v7, v115, v15
	v_fmac_f32_e32 v7, v116, v16
	v_fmac_f32_e32 v7, v117, v17
	ds_read_b128 v[14:17], v13 offset:192
	ds_read_b128 v[22:25], v13 offset:8272
	s_waitcnt lgkmcnt(2)
	v_fmac_f32_e32 v9, v114, v18
	v_fmac_f32_e32 v9, v115, v19
	v_fmac_f32_e32 v9, v116, v20
	v_fmac_f32_e32 v9, v117, v21
	ds_read_b128 v[18:21], v13 offset:4288
	s_waitcnt lgkmcnt(2)
	v_fmac_f32_e32 v7, v118, v14
	v_fmac_f32_e32 v7, v119, v15
	s_waitcnt lgkmcnt(1)
	v_fmac_f32_e32 v12, v90, v22
	v_fmac_f32_e32 v7, v120, v16
	v_fmac_f32_e32 v12, v91, v23
	v_fmac_f32_e32 v7, v121, v17
	ds_read_b128 v[14:17], v13 offset:208
	v_fmac_f32_e32 v12, v92, v24
	v_fmac_f32_e32 v12, v93, v25
	ds_read_b128 v[22:25], v13 offset:8288
	s_waitcnt lgkmcnt(2)
	v_fmac_f32_e32 v9, v118, v18
	v_fmac_f32_e32 v9, v119, v19
	v_fmac_f32_e32 v9, v120, v20
	v_fmac_f32_e32 v9, v121, v21
	ds_read_b128 v[18:21], v13 offset:4304
	s_waitcnt lgkmcnt(2)
	v_fmac_f32_e32 v7, v122, v14
	v_fmac_f32_e32 v7, v123, v15
	s_waitcnt lgkmcnt(1)
	v_fmac_f32_e32 v12, v94, v22
	v_fmac_f32_e32 v7, v124, v16
	v_fmac_f32_e32 v12, v95, v23
	v_fmac_f32_e32 v7, v125, v17
	ds_read_b128 v[14:17], v13 offset:224
	v_fmac_f32_e32 v12, v96, v24
	v_fmac_f32_e32 v12, v97, v25
	ds_read_b128 v[22:25], v13 offset:8304
	s_waitcnt lgkmcnt(2)
	v_fmac_f32_e32 v9, v122, v18
	v_fmac_f32_e32 v9, v123, v19
	v_fmac_f32_e32 v9, v124, v20
	v_fmac_f32_e32 v9, v125, v21
	ds_read_b128 v[18:21], v13 offset:4320
	s_waitcnt lgkmcnt(2)
	v_fmac_f32_e32 v7, v126, v14
	v_fmac_f32_e32 v7, v127, v15
	s_waitcnt lgkmcnt(1)
	v_fmac_f32_e32 v12, v98, v22
	v_fmac_f32_e32 v7, v128, v16
	v_fmac_f32_e32 v12, v99, v23
	v_fmac_f32_e32 v7, v129, v17
	ds_read_b128 v[14:17], v13 offset:240
	v_fmac_f32_e32 v12, v100, v24
	v_fmac_f32_e32 v12, v101, v25
	ds_read_b128 v[22:25], v13 offset:8320
	s_waitcnt lgkmcnt(2)
	v_fmac_f32_e32 v9, v126, v18
	v_fmac_f32_e32 v9, v127, v19
	v_fmac_f32_e32 v9, v128, v20
	v_fmac_f32_e32 v9, v129, v21
	ds_read_b128 v[18:21], v13 offset:4336
	s_waitcnt lgkmcnt(2)
	v_fmac_f32_e32 v7, v130, v14
	v_fmac_f32_e32 v7, v131, v15
	s_waitcnt lgkmcnt(1)
	v_fmac_f32_e32 v12, v102, v22
	v_fmac_f32_e32 v12, v103, v23
	s_nop 0
	v_fmac_f32_e32 v12, v104, v24
	v_fmac_f32_e32 v12, v105, v25
	ds_read_b128 v[22:25], v13 offset:8336
	s_waitcnt lgkmcnt(0)
	v_fmac_f32_e32 v12, v106, v22
	v_fmac_f32_e32 v12, v107, v23
	s_nop 0
	v_fmac_f32_e32 v12, v108, v24
	v_fmac_f32_e32 v12, v109, v25
	ds_read_b128 v[22:25], v13 offset:8352
	s_waitcnt lgkmcnt(0)
	v_fmac_f32_e32 v12, v110, v22
	v_fmac_f32_e32 v12, v111, v23
	s_nop 0
	v_fmac_f32_e32 v12, v112, v24
	v_fmac_f32_e32 v12, v113, v25
	ds_read_b128 v[22:25], v13 offset:8368
	s_waitcnt lgkmcnt(0)
	v_fmac_f32_e32 v12, v114, v22
	v_fmac_f32_e32 v12, v115, v23
	s_nop 0
	v_fmac_f32_e32 v12, v116, v24
	v_fmac_f32_e32 v12, v117, v25
	ds_read_b128 v[22:25], v13 offset:8384
	s_waitcnt lgkmcnt(0)
	v_fmac_f32_e32 v12, v118, v22
	v_fmac_f32_e32 v12, v119, v23
	s_nop 0
	v_fmac_f32_e32 v12, v120, v24
	v_fmac_f32_e32 v12, v121, v25
	ds_read_b128 v[22:25], v13 offset:8400
	s_waitcnt lgkmcnt(0)
	v_fmac_f32_e32 v12, v122, v22
	v_fmac_f32_e32 v12, v123, v23
	s_nop 0
	v_fmac_f32_e32 v12, v124, v24
	v_fmac_f32_e32 v12, v125, v25
	ds_read_b128 v[22:25], v13 offset:8416
	s_waitcnt lgkmcnt(0)
	v_fmac_f32_e32 v12, v126, v22
	v_fmac_f32_e32 v12, v127, v23
	v_fmac_f32_e32 v12, v128, v24
	v_fmac_f32_e32 v12, v129, v25
	ds_read_b128 v[22:25], v13 offset:8432
	v_fmac_f32_e32 v9, v130, v18
	s_waitcnt lgkmcnt(0)
	v_fmac_f32_e32 v12, v130, v22
	v_fmac_f32_e32 v9, v131, v19
	s_nop 0
	v_fmac_f32_e32 v12, v131, v23
	v_fmac_f32_e32 v7, v132, v16
	v_fmac_f32_e32 v9, v132, v20
	v_fmac_f32_e32 v12, v132, v24
	v_fmac_f32_e32 v7, v133, v17
	v_fmac_f32_e32 v9, v133, v21
	v_fmac_f32_e32 v12, v133, v25
	ds_read_b128 v[14:17], v13 offset:256
	ds_read_b128 v[18:21], v13 offset:4352
	ds_read_b128 v[22:25], v13 offset:8448
	s_waitcnt lgkmcnt(2)
	v_fmac_f32_e32 v7, v134, v14
	s_waitcnt vmcnt(62)
	v_fmac_f32_e32 v7, v135, v15
	s_waitcnt vmcnt(61)
	v_fmac_f32_e32 v7, v136, v16
	s_waitcnt vmcnt(60)
	v_fmac_f32_e32 v7, v137, v17
	ds_read_b128 v[14:17], v13 offset:272
	s_waitcnt lgkmcnt(2)
	v_fmac_f32_e32 v9, v134, v18
	v_fmac_f32_e32 v9, v135, v19
	v_fmac_f32_e32 v9, v136, v20
	v_fmac_f32_e32 v9, v137, v21
	ds_read_b128 v[18:21], v13 offset:4368
	s_waitcnt lgkmcnt(1)
	s_waitcnt vmcnt(59)
	v_fmac_f32_e32 v7, v138, v14
	s_waitcnt vmcnt(58)
	v_fmac_f32_e32 v7, v139, v15
	v_fmac_f32_e32 v12, v134, v22
	s_waitcnt vmcnt(57)
	v_fmac_f32_e32 v7, v140, v16
	v_fmac_f32_e32 v12, v135, v23
	s_waitcnt vmcnt(56)
	v_fmac_f32_e32 v7, v141, v17
	ds_read_b128 v[14:17], v13 offset:288
	v_fmac_f32_e32 v12, v136, v24
	v_fmac_f32_e32 v12, v137, v25
	s_waitcnt lgkmcnt(1)
	v_fmac_f32_e32 v9, v138, v18
	ds_read_b128 v[22:25], v13 offset:8464
	v_fmac_f32_e32 v9, v139, v19
	v_fmac_f32_e32 v9, v140, v20
	v_fmac_f32_e32 v9, v141, v21
	ds_read_b128 v[18:21], v13 offset:4384
	s_waitcnt lgkmcnt(2)
	s_waitcnt vmcnt(55)
	v_fmac_f32_e32 v7, v142, v14
	s_waitcnt vmcnt(54)
	v_fmac_f32_e32 v7, v143, v15
	s_waitcnt lgkmcnt(1)
	v_fmac_f32_e32 v12, v138, v22
	s_waitcnt vmcnt(53)
	v_fmac_f32_e32 v7, v144, v16
	v_fmac_f32_e32 v12, v139, v23
	s_waitcnt vmcnt(52)
	v_fmac_f32_e32 v7, v145, v17
	ds_read_b128 v[14:17], v13 offset:304
	v_fmac_f32_e32 v12, v140, v24
	v_fmac_f32_e32 v12, v141, v25
	s_waitcnt lgkmcnt(1)
	v_fmac_f32_e32 v9, v142, v18
	ds_read_b128 v[22:25], v13 offset:8480
	v_fmac_f32_e32 v9, v143, v19
	v_fmac_f32_e32 v9, v144, v20
	v_fmac_f32_e32 v9, v145, v21
	ds_read_b128 v[18:21], v13 offset:4400
	s_waitcnt lgkmcnt(2)
	s_waitcnt vmcnt(51)
	v_fmac_f32_e32 v7, v146, v14
	s_waitcnt vmcnt(50)
	v_fmac_f32_e32 v7, v147, v15
	s_waitcnt lgkmcnt(1)
	v_fmac_f32_e32 v12, v142, v22
	s_waitcnt vmcnt(49)
	v_fmac_f32_e32 v7, v148, v16
	v_fmac_f32_e32 v12, v143, v23
	s_waitcnt vmcnt(48)
	v_fmac_f32_e32 v7, v149, v17
	ds_read_b128 v[14:17], v13 offset:320
	v_fmac_f32_e32 v12, v144, v24
	v_fmac_f32_e32 v12, v145, v25
	s_waitcnt lgkmcnt(1)
	v_fmac_f32_e32 v9, v146, v18
	ds_read_b128 v[22:25], v13 offset:8496
	v_fmac_f32_e32 v9, v147, v19
	v_fmac_f32_e32 v9, v148, v20
	v_fmac_f32_e32 v9, v149, v21
	ds_read_b128 v[18:21], v13 offset:4416
	s_waitcnt lgkmcnt(2)
	s_waitcnt vmcnt(47)
	v_fmac_f32_e32 v7, v150, v14
	s_waitcnt vmcnt(46)
	v_fmac_f32_e32 v7, v151, v15
	s_waitcnt lgkmcnt(1)
	v_fmac_f32_e32 v12, v146, v22
	s_waitcnt vmcnt(45)
	v_fmac_f32_e32 v7, v152, v16
	v_fmac_f32_e32 v12, v147, v23
	s_waitcnt vmcnt(44)
	v_fmac_f32_e32 v7, v153, v17
	ds_read_b128 v[14:17], v13 offset:336
	v_fmac_f32_e32 v12, v148, v24
	v_fmac_f32_e32 v12, v149, v25
	s_waitcnt lgkmcnt(1)
	v_fmac_f32_e32 v9, v150, v18
	ds_read_b128 v[22:25], v13 offset:8512
	v_fmac_f32_e32 v9, v151, v19
	v_fmac_f32_e32 v9, v152, v20
	v_fmac_f32_e32 v9, v153, v21
	ds_read_b128 v[18:21], v13 offset:4432
	s_waitcnt lgkmcnt(2)
	s_waitcnt vmcnt(43)
	v_fmac_f32_e32 v7, v154, v14
	s_waitcnt vmcnt(42)
	v_fmac_f32_e32 v7, v155, v15
	s_waitcnt lgkmcnt(1)
	v_fmac_f32_e32 v12, v150, v22
	s_waitcnt vmcnt(41)
	v_fmac_f32_e32 v7, v156, v16
	v_fmac_f32_e32 v12, v151, v23
	s_waitcnt vmcnt(40)
	v_fmac_f32_e32 v7, v157, v17
	ds_read_b128 v[14:17], v13 offset:352
	v_fmac_f32_e32 v12, v152, v24
	v_fmac_f32_e32 v12, v153, v25
	s_waitcnt lgkmcnt(1)
	v_fmac_f32_e32 v9, v154, v18
	ds_read_b128 v[22:25], v13 offset:8528
	v_fmac_f32_e32 v9, v155, v19
	v_fmac_f32_e32 v9, v156, v20
	v_fmac_f32_e32 v9, v157, v21
	ds_read_b128 v[18:21], v13 offset:4448
	s_waitcnt lgkmcnt(2)
	s_waitcnt vmcnt(39)
	v_fmac_f32_e32 v7, v158, v14
	s_waitcnt vmcnt(38)
	v_fmac_f32_e32 v7, v159, v15
	s_waitcnt lgkmcnt(1)
	v_fmac_f32_e32 v12, v154, v22
	s_waitcnt vmcnt(37)
	v_fmac_f32_e32 v7, v160, v16
	v_fmac_f32_e32 v12, v155, v23
	s_waitcnt vmcnt(36)
	v_fmac_f32_e32 v7, v161, v17
	ds_read_b128 v[14:17], v13 offset:368
	v_fmac_f32_e32 v12, v156, v24
	v_fmac_f32_e32 v12, v157, v25
	s_waitcnt lgkmcnt(1)
	v_fmac_f32_e32 v9, v158, v18
	ds_read_b128 v[22:25], v13 offset:8544
	v_fmac_f32_e32 v9, v159, v19
	v_fmac_f32_e32 v9, v160, v20
	v_fmac_f32_e32 v9, v161, v21
	ds_read_b128 v[18:21], v13 offset:4464
	s_waitcnt lgkmcnt(2)
	s_waitcnt vmcnt(35)
	v_fmac_f32_e32 v7, v162, v14
	s_waitcnt vmcnt(34)
	v_fmac_f32_e32 v7, v163, v15
	s_waitcnt lgkmcnt(1)
	v_fmac_f32_e32 v12, v158, v22
	v_fmac_f32_e32 v12, v159, v23
	s_nop 0
	v_fmac_f32_e32 v12, v160, v24
	v_fmac_f32_e32 v12, v161, v25
	ds_read_b128 v[22:25], v13 offset:8560
	s_waitcnt lgkmcnt(0)
	v_fmac_f32_e32 v12, v162, v22
	v_fmac_f32_e32 v12, v163, v23
	s_nop 0
	s_waitcnt vmcnt(33)
	v_fmac_f32_e32 v12, v164, v24
	s_waitcnt vmcnt(32)
	v_fmac_f32_e32 v12, v165, v25
	v_fmac_f32_e32 v7, v164, v16
	v_fmac_f32_e32 v7, v165, v17
	v_fmac_f32_e32 v9, v162, v18
	s_nop 0
	v_fmac_f32_e32 v9, v163, v19
	v_fmac_f32_e32 v9, v164, v20
	v_fmac_f32_e32 v9, v165, v21
	ds_read_b128 v[50:53], v13 offset:4480
	ds_read_b128 v[46:49], v13 offset:384
	ds_read_b128 v[54:57], v13 offset:8576
	s_waitcnt lgkmcnt(2)
	s_waitcnt vmcnt(31)
	v_fmac_f32_e32 v9, v166, v50
	s_waitcnt vmcnt(30)
	v_fmac_f32_e32 v9, v167, v51
	s_waitcnt vmcnt(29)
	v_fmac_f32_e32 v9, v168, v52
	s_waitcnt lgkmcnt(1)
	v_fmac_f32_e32 v7, v166, v46
	s_waitcnt lgkmcnt(0)
	v_fmac_f32_e32 v12, v166, v54
	v_fmac_f32_e32 v7, v167, v47
	v_fmac_f32_e32 v12, v167, v55
	v_fmac_f32_e32 v7, v168, v48
	v_fmac_f32_e32 v12, v168, v56
	s_waitcnt vmcnt(28)
	v_fmac_f32_e32 v7, v169, v49
	v_fmac_f32_e32 v9, v169, v53
	v_fmac_f32_e32 v12, v169, v57
	ds_read_b128 v[44:47], v13 offset:400
	ds_read_b128 v[48:51], v13 offset:4496
	ds_read_b128 v[52:55], v13 offset:8592
	s_waitcnt lgkmcnt(2)
	s_waitcnt vmcnt(27)
	v_fmac_f32_e32 v7, v170, v44
	s_waitcnt vmcnt(26)
	v_fmac_f32_e32 v7, v171, v45
	s_waitcnt vmcnt(25)
	v_fmac_f32_e32 v7, v172, v46
	s_waitcnt vmcnt(24)
	v_fmac_f32_e32 v7, v173, v47
	ds_read_b128 v[44:47], v13 offset:416
	s_waitcnt lgkmcnt(2)
	v_fmac_f32_e32 v9, v170, v48
	v_fmac_f32_e32 v9, v171, v49
	v_fmac_f32_e32 v9, v172, v50
	v_fmac_f32_e32 v9, v173, v51
	ds_read_b128 v[48:51], v13 offset:4512
	s_waitcnt lgkmcnt(1)
	s_waitcnt vmcnt(23)
	v_fmac_f32_e32 v7, v174, v44
	s_waitcnt vmcnt(22)
	v_fmac_f32_e32 v7, v175, v45
	s_waitcnt vmcnt(21)
	v_fmac_f32_e32 v7, v176, v46
	s_waitcnt vmcnt(20)
	v_fmac_f32_e32 v7, v177, v47
	ds_read_b128 v[44:47], v13 offset:432
	s_waitcnt lgkmcnt(1)
	v_fmac_f32_e32 v9, v174, v48
	v_fmac_f32_e32 v9, v175, v49
	v_fmac_f32_e32 v9, v176, v50
	v_fmac_f32_e32 v9, v177, v51
	ds_read_b128 v[48:51], v13 offset:4528
	s_waitcnt lgkmcnt(1)
	s_waitcnt vmcnt(19)
	v_fmac_f32_e32 v7, v178, v44
	s_waitcnt vmcnt(18)
	v_fmac_f32_e32 v7, v179, v45
	s_waitcnt vmcnt(17)
	v_fmac_f32_e32 v7, v180, v46
	s_waitcnt vmcnt(16)
	v_fmac_f32_e32 v7, v181, v47
	ds_read_b128 v[44:47], v13 offset:448
	s_waitcnt lgkmcnt(1)
	v_fmac_f32_e32 v9, v178, v48
	v_fmac_f32_e32 v9, v179, v49
	v_fmac_f32_e32 v9, v180, v50
	v_fmac_f32_e32 v9, v181, v51
	ds_read_b128 v[48:51], v13 offset:4544
	s_waitcnt lgkmcnt(1)
	s_waitcnt vmcnt(15)
	v_fmac_f32_e32 v7, v182, v44
	s_waitcnt vmcnt(14)
	v_fmac_f32_e32 v7, v183, v45
	s_waitcnt vmcnt(13)
	v_fmac_f32_e32 v7, v184, v46
	s_waitcnt vmcnt(12)
	v_fmac_f32_e32 v7, v185, v47
	ds_read_b128 v[44:47], v13 offset:8656
	v_fmac_f32_e32 v12, v170, v52
	v_fmac_f32_e32 v12, v171, v53
	v_fmac_f32_e32 v12, v172, v54
	v_fmac_f32_e32 v12, v173, v55
	ds_read_b128 v[52:55], v13 offset:8608
	s_waitcnt lgkmcnt(2)
	v_fmac_f32_e32 v9, v182, v48
	v_fmac_f32_e32 v9, v183, v49
	v_fmac_f32_e32 v9, v184, v50
	v_fmac_f32_e32 v9, v185, v51
	s_waitcnt lgkmcnt(0)
	v_fmac_f32_e32 v12, v174, v52
	v_fmac_f32_e32 v12, v175, v53
	v_fmac_f32_e32 v12, v176, v54
	v_fmac_f32_e32 v12, v177, v55
	ds_read_b128 v[52:55], v13 offset:8624
	s_waitcnt lgkmcnt(0)
	v_fmac_f32_e32 v12, v178, v52
	v_fmac_f32_e32 v12, v179, v53
	v_fmac_f32_e32 v12, v180, v54
	v_fmac_f32_e32 v12, v181, v55
	ds_read_b128 v[52:55], v13 offset:8640
	s_waitcnt lgkmcnt(0)
	v_fmac_f32_e32 v12, v182, v52
	v_fmac_f32_e32 v12, v183, v53
	v_fmac_f32_e32 v12, v184, v54
	v_fmac_f32_e32 v12, v185, v55
	ds_read_b128 v[36:39], v13 offset:464
	ds_read_b128 v[40:43], v13 offset:4560
	s_waitcnt vmcnt(11)
	v_fmac_f32_e32 v12, v186, v44
	s_waitcnt vmcnt(10)
	v_fmac_f32_e32 v12, v187, v45
	s_waitcnt vmcnt(9)
	v_fmac_f32_e32 v12, v188, v46
	s_waitcnt lgkmcnt(1)
	v_fmac_f32_e32 v7, v186, v36
	s_waitcnt lgkmcnt(0)
	v_fmac_f32_e32 v9, v186, v40
	v_fmac_f32_e32 v7, v187, v37
	v_fmac_f32_e32 v9, v187, v41
	v_fmac_f32_e32 v7, v188, v38
	v_fmac_f32_e32 v9, v188, v42
	ds_read_b128 v[20:23], v13 offset:480
	s_waitcnt vmcnt(8)
	v_fmac_f32_e32 v7, v189, v39
	v_fmac_f32_e32 v9, v189, v43
	ds_read_b128 v[36:39], v13 offset:4576
	ds_read_b128 v[40:43], v13 offset:8672
	s_waitcnt lgkmcnt(2)
	s_waitcnt vmcnt(7)
	v_fmac_f32_e32 v7, v190, v20
	v_fmac_f32_e32 v12, v189, v47
	s_waitcnt vmcnt(6)
	v_fmac_f32_e32 v7, v191, v21
	s_waitcnt lgkmcnt(1)
	v_fmac_f32_e32 v9, v190, v36
	s_waitcnt lgkmcnt(0)
	v_fmac_f32_e32 v12, v190, v40
	s_waitcnt vmcnt(5)
	v_fmac_f32_e32 v7, v192, v22
	v_fmac_f32_e32 v9, v191, v37
	v_fmac_f32_e32 v12, v191, v41
	s_waitcnt vmcnt(4)
	v_fmac_f32_e32 v7, v193, v23
	ds_read_b128 v[20:23], v13 offset:496
	ds_read_b128 v[24:27], v13 offset:4592
	v_fmac_f32_e32 v9, v192, v38
	v_fmac_f32_e32 v12, v192, v42
	ds_read_b128 v[28:31], v13 offset:8688
	v_fmac_f32_e32 v9, v193, v39
	v_fmac_f32_e32 v12, v193, v43
	s_waitcnt lgkmcnt(2)
	s_waitcnt vmcnt(3)
	v_fmac_f32_e32 v7, v194, v20
	s_waitcnt lgkmcnt(1)
	v_fmac_f32_e32 v9, v194, v24
	s_waitcnt lgkmcnt(0)
	v_fmac_f32_e32 v12, v194, v28
	s_waitcnt vmcnt(2)
	v_fmac_f32_e32 v7, v195, v21
	v_fmac_f32_e32 v9, v195, v25
	v_fmac_f32_e32 v12, v195, v29
	s_waitcnt vmcnt(1)
	v_fmac_f32_e32 v7, v196, v22
	v_fmac_f32_e32 v9, v196, v26
	v_fmac_f32_e32 v12, v196, v30
	s_waitcnt vmcnt(0)
	v_fmac_f32_e32 v7, v197, v23
	v_fmac_f32_e32 v9, v197, v27
	v_fmac_f32_e32 v12, v197, v31
	ds_write2st64_b32 v3, v7, v9 offset0:48 offset1:49
	ds_write_b32 v3, v12 offset:12800
	s_waitcnt lgkmcnt(0)
	s_barrier
	s_and_saveexec_b64 s[4:5], s[2:3]
	s_cbranch_execz .LBB0_1024
	s_mul_i32 s14, s7, 0x2400
	s_add_i32 s14, s14, s13
	v_add_u32_e32 v10, s14, v6
	v_ashrrev_i32_e32 v11, 31, v10
	v_lshl_add_u64 v[10:11], v[10:11], 2, s[10:11]
	global_load_dword v7, v[10:11], off
	ds_read2st64_b32 v[10:11], v5 offset0:48 offset1:51
	ds_read2st64_b32 v[12:13], v5 offset0:54 offset1:57
	ds_read2st64_b32 v[14:15], v5 offset0:60 offset1:63
	ds_read2st64_b32 v[16:17], v5 offset0:66 offset1:69
	v_mad_u64_u32 v[18:19], s[14:15], s7, 3, v[4:5]
	v_mov_b64_e32 v[20:21], s[68:69]
	v_mad_i64_i32 v[18:19], s[14:15], v18, s87, v[20:21]
	v_mov_b32_e32 v9, v1
	v_lshl_add_u64 v[18:19], v[18:19], 0, s[80:81]
	s_waitcnt vmcnt(0) lgkmcnt(3)
	v_add_f32_e32 v7, v7, v10
	v_add_f32_e32 v7, v7, v11
	s_waitcnt lgkmcnt(2)
	v_add_f32_e32 v7, v7, v12
	v_add_f32_e32 v7, v7, v13
	s_waitcnt lgkmcnt(1)
	v_add_f32_e32 v7, v7, v14
	v_add_f32_e32 v7, v7, v15
	s_waitcnt lgkmcnt(0)
	v_add_f32_e32 v7, v7, v16
	v_add_f32_e32 v7, v7, v17
	v_lshl_add_u64 v[10:11], v[18:19], 0, v[8:9]
	global_store_dword v[10:11], v7, off
	s_branch .LBB0_1024

.LBB0_1143:
	s_or_b64 exec, exec, s[2:3]
	s_waitcnt lgkmcnt(0)
	s_barrier
	s_load_dwordx4 s[8:11], s[0:1], 0x20
	v_readlane_b32 s2, v254, 41
	v_readlane_b32 s3, v254, 42
	s_add_i32 s2, s2, s14
	s_add_i32 s5, s2, 0x100
	s_lshl_b32 s2, s6, 7
	s_mul_i32 s3, s6, 0x480000
	s_mul_hi_i32 s2, s2, 0x9000
	s_waitcnt lgkmcnt(0)
	s_add_u32 s8, s8, s3
	s_addc_u32 s9, s9, s2
	s_lshl_b32 s2, s6, 9
	s_mulk_i32 s6, 0x300
	v_and_b32_e32 v3, 63, v4
	s_add_i32 s4, s2, 0
	s_add_i32 s2, s6, 0
	v_lshl_add_u32 v6, v3, 2, s2
	s_movk_i32 s2, 0xc0
	v_cmp_gt_u32_e32 vcc, 36, v3
	v_cmp_gt_i32_e64 s[6:7], s2, v4
	s_and_b64 s[2:3], s[6:7], vcc
	s_ashr_i32 s6, s5, 8
	s_and_b32 s7, s14, 0xff
	s_mul_i32 s12, s6, 0x2400000
	s_mul_i32 s7, s7, 36
	s_mul_hi_i32 s5, s6, 0x2400000
	s_add_u32 s8, s8, s12
	s_addc_u32 s5, s9, s5
	s_lshl_b32 s80, s7, 2
	v_min_u32_e32 v0, 35, v3
	s_add_u32 s8, s8, s80
	s_addc_u32 s9, s5, 0
	v_lshlrev_b32_e32 v0, 2, v0
	v_lshl_add_u64 v[4:5], s[8:9], 0, v[0:1]
	global_load_dword v66, v[4:5], off nt
	s_mov_b64 s[98:99], 0x9000
	v_lshl_add_u64 v[8:9], v[4:5], 0, s[98:99]
	global_load_dword v67, v[8:9], off nt
	s_mov_b64 s[98:99], 0x12000
	v_lshl_add_u64 v[8:9], v[4:5], 0, s[98:99]
	global_load_dword v68, v[8:9], off nt
	s_mov_b64 s[98:99], 0x1b000
	v_lshl_add_u64 v[8:9], v[4:5], 0, s[98:99]
	global_load_dword v69, v[8:9], off nt
	s_mov_b64 s[98:99], 0x24000
	v_lshl_add_u64 v[8:9], v[4:5], 0, s[98:99]
	global_load_dword v70, v[8:9], off nt
	s_mov_b64 s[98:99], 0x2d000
	v_lshl_add_u64 v[8:9], v[4:5], 0, s[98:99]
	global_load_dword v71, v[8:9], off nt
	s_mov_b64 s[98:99], 0x36000
	v_lshl_add_u64 v[8:9], v[4:5], 0, s[98:99]
	global_load_dword v72, v[8:9], off nt
	s_mov_b64 s[98:99], 0x3f000
	v_lshl_add_u64 v[8:9], v[4:5], 0, s[98:99]
	global_load_dword v73, v[8:9], off nt
	s_mov_b64 s[98:99], 0x48000
	v_lshl_add_u64 v[8:9], v[4:5], 0, s[98:99]
	global_load_dword v74, v[8:9], off nt
	s_mov_b64 s[98:99], 0x51000
	v_lshl_add_u64 v[8:9], v[4:5], 0, s[98:99]
	global_load_dword v75, v[8:9], off nt
	s_mov_b64 s[98:99], 0x5a000
	v_lshl_add_u64 v[8:9], v[4:5], 0, s[98:99]
	global_load_dword v76, v[8:9], off nt
	s_mov_b64 s[98:99], 0x63000
	v_lshl_add_u64 v[8:9], v[4:5], 0, s[98:99]
	global_load_dword v77, v[8:9], off nt
	s_mov_b64 s[98:99], 0x6c000
	v_lshl_add_u64 v[8:9], v[4:5], 0, s[98:99]
	global_load_dword v78, v[8:9], off nt
	s_mov_b64 s[98:99], 0x75000
	v_lshl_add_u64 v[8:9], v[4:5], 0, s[98:99]
	global_load_dword v79, v[8:9], off nt
	s_mov_b64 s[98:99], 0x7e000
	v_lshl_add_u64 v[8:9], v[4:5], 0, s[98:99]
	global_load_dword v80, v[8:9], off nt
	s_mov_b64 s[98:99], 0x87000
	v_lshl_add_u64 v[8:9], v[4:5], 0, s[98:99]
	global_load_dword v81, v[8:9], off nt
	s_mov_b64 s[98:99], 0x90000
	v_lshl_add_u64 v[8:9], v[4:5], 0, s[98:99]
	global_load_dword v82, v[8:9], off nt
	s_mov_b64 s[98:99], 0x99000
	v_lshl_add_u64 v[8:9], v[4:5], 0, s[98:99]
	global_load_dword v83, v[8:9], off nt
	s_mov_b64 s[98:99], 0xa2000
	v_lshl_add_u64 v[8:9], v[4:5], 0, s[98:99]
	global_load_dword v84, v[8:9], off nt
	s_mov_b64 s[98:99], 0xab000
	v_lshl_add_u64 v[8:9], v[4:5], 0, s[98:99]
	global_load_dword v85, v[8:9], off nt
	s_mov_b64 s[98:99], 0xb4000
	v_lshl_add_u64 v[8:9], v[4:5], 0, s[98:99]
	global_load_dword v86, v[8:9], off nt
	s_mov_b64 s[98:99], 0xbd000
	v_lshl_add_u64 v[8:9], v[4:5], 0, s[98:99]
	global_load_dword v87, v[8:9], off nt
	s_mov_b64 s[98:99], 0xc6000
	v_lshl_add_u64 v[8:9], v[4:5], 0, s[98:99]
	global_load_dword v88, v[8:9], off nt
	s_mov_b64 s[98:99], 0xcf000
	v_lshl_add_u64 v[8:9], v[4:5], 0, s[98:99]
	global_load_dword v89, v[8:9], off nt
	s_mov_b64 s[98:99], 0xd8000
	v_lshl_add_u64 v[8:9], v[4:5], 0, s[98:99]
	global_load_dword v90, v[8:9], off nt
	s_mov_b64 s[98:99], 0xe1000
	v_lshl_add_u64 v[8:9], v[4:5], 0, s[98:99]
	global_load_dword v91, v[8:9], off nt
	s_mov_b64 s[98:99], 0xea000
	v_lshl_add_u64 v[8:9], v[4:5], 0, s[98:99]
	global_load_dword v92, v[8:9], off nt
	s_mov_b64 s[98:99], 0xf3000
	v_lshl_add_u64 v[8:9], v[4:5], 0, s[98:99]
	global_load_dword v93, v[8:9], off nt
	s_mov_b64 s[98:99], 0xfc000
	v_lshl_add_u64 v[8:9], v[4:5], 0, s[98:99]
	global_load_dword v94, v[8:9], off nt
	s_mov_b64 s[98:99], 0x105000
	v_lshl_add_u64 v[8:9], v[4:5], 0, s[98:99]
	global_load_dword v95, v[8:9], off nt
	s_mov_b64 s[98:99], 0x10e000
	v_lshl_add_u64 v[8:9], v[4:5], 0, s[98:99]
	global_load_dword v96, v[8:9], off nt
	s_mov_b64 s[98:99], 0x117000
	v_lshl_add_u64 v[8:9], v[4:5], 0, s[98:99]
	global_load_dword v97, v[8:9], off nt
	s_mov_b64 s[98:99], 0x120000
	v_lshl_add_u64 v[8:9], v[4:5], 0, s[98:99]
	global_load_dword v98, v[8:9], off nt
	s_mov_b64 s[98:99], 0x129000
	v_lshl_add_u64 v[8:9], v[4:5], 0, s[98:99]
	global_load_dword v99, v[8:9], off nt
	s_mov_b64 s[98:99], 0x132000
	v_lshl_add_u64 v[8:9], v[4:5], 0, s[98:99]
	global_load_dword v100, v[8:9], off nt
	s_mov_b64 s[98:99], 0x13b000
	v_lshl_add_u64 v[8:9], v[4:5], 0, s[98:99]
	global_load_dword v101, v[8:9], off nt
	s_mov_b64 s[98:99], 0x144000
	v_lshl_add_u64 v[8:9], v[4:5], 0, s[98:99]
	global_load_dword v102, v[8:9], off nt
	s_mov_b64 s[98:99], 0x14d000
	v_lshl_add_u64 v[8:9], v[4:5], 0, s[98:99]
	global_load_dword v103, v[8:9], off nt
	s_mov_b64 s[98:99], 0x156000
	v_lshl_add_u64 v[8:9], v[4:5], 0, s[98:99]
	global_load_dword v104, v[8:9], off nt
	s_mov_b64 s[98:99], 0x15f000
	v_lshl_add_u64 v[8:9], v[4:5], 0, s[98:99]
	global_load_dword v105, v[8:9], off nt
	s_mov_b64 s[98:99], 0x168000
	v_lshl_add_u64 v[8:9], v[4:5], 0, s[98:99]
	global_load_dword v106, v[8:9], off nt
	s_mov_b64 s[98:99], 0x171000
	v_lshl_add_u64 v[8:9], v[4:5], 0, s[98:99]
	global_load_dword v107, v[8:9], off nt
	s_mov_b64 s[98:99], 0x17a000
	v_lshl_add_u64 v[8:9], v[4:5], 0, s[98:99]
	global_load_dword v108, v[8:9], off nt
	s_mov_b64 s[98:99], 0x183000
	v_lshl_add_u64 v[8:9], v[4:5], 0, s[98:99]
	global_load_dword v109, v[8:9], off nt
	s_mov_b64 s[98:99], 0x18c000
	v_lshl_add_u64 v[8:9], v[4:5], 0, s[98:99]
	global_load_dword v110, v[8:9], off nt
	s_mov_b64 s[98:99], 0x195000
	v_lshl_add_u64 v[8:9], v[4:5], 0, s[98:99]
	global_load_dword v111, v[8:9], off nt
	s_mov_b64 s[98:99], 0x19e000
	v_lshl_add_u64 v[8:9], v[4:5], 0, s[98:99]
	global_load_dword v112, v[8:9], off nt
	s_mov_b64 s[98:99], 0x1a7000
	v_lshl_add_u64 v[8:9], v[4:5], 0, s[98:99]
	global_load_dword v113, v[8:9], off nt
	s_mov_b64 s[98:99], 0x1b0000
	v_lshl_add_u64 v[8:9], v[4:5], 0, s[98:99]
	global_load_dword v114, v[8:9], off nt
	s_mov_b64 s[98:99], 0x1b9000
	v_lshl_add_u64 v[8:9], v[4:5], 0, s[98:99]
	global_load_dword v115, v[8:9], off nt
	s_mov_b64 s[98:99], 0x1c2000
	v_lshl_add_u64 v[8:9], v[4:5], 0, s[98:99]
	global_load_dword v116, v[8:9], off nt
	s_mov_b64 s[98:99], 0x1cb000
	v_lshl_add_u64 v[8:9], v[4:5], 0, s[98:99]
	global_load_dword v117, v[8:9], off nt
	s_mov_b64 s[98:99], 0x1d4000
	v_lshl_add_u64 v[8:9], v[4:5], 0, s[98:99]
	global_load_dword v118, v[8:9], off nt
	s_mov_b64 s[98:99], 0x1dd000
	v_lshl_add_u64 v[8:9], v[4:5], 0, s[98:99]
	global_load_dword v119, v[8:9], off nt
	s_mov_b64 s[98:99], 0x1e6000
	v_lshl_add_u64 v[8:9], v[4:5], 0, s[98:99]
	global_load_dword v120, v[8:9], off nt
	s_mov_b64 s[98:99], 0x1ef000
	v_lshl_add_u64 v[8:9], v[4:5], 0, s[98:99]
	global_load_dword v121, v[8:9], off nt
	s_mov_b64 s[98:99], 0x1f8000
	v_lshl_add_u64 v[8:9], v[4:5], 0, s[98:99]
	global_load_dword v122, v[8:9], off nt
	s_mov_b64 s[98:99], 0x201000
	v_lshl_add_u64 v[8:9], v[4:5], 0, s[98:99]
	global_load_dword v123, v[8:9], off nt
	s_mov_b64 s[98:99], 0x20a000
	v_lshl_add_u64 v[8:9], v[4:5], 0, s[98:99]
	global_load_dword v124, v[8:9], off nt
	s_mov_b64 s[98:99], 0x213000
	v_lshl_add_u64 v[8:9], v[4:5], 0, s[98:99]
	global_load_dword v125, v[8:9], off nt
	s_mov_b64 s[98:99], 0x21c000
	v_lshl_add_u64 v[8:9], v[4:5], 0, s[98:99]
	global_load_dword v126, v[8:9], off nt
	s_mov_b64 s[98:99], 0x225000
	v_lshl_add_u64 v[8:9], v[4:5], 0, s[98:99]
	global_load_dword v127, v[8:9], off nt
	s_mov_b64 s[98:99], 0x22e000
	v_lshl_add_u64 v[8:9], v[4:5], 0, s[98:99]
	global_load_dword v128, v[8:9], off nt
	s_mov_b64 s[98:99], 0x237000
	v_lshl_add_u64 v[8:9], v[4:5], 0, s[98:99]
	global_load_dword v129, v[8:9], off nt
	s_mov_b64 s[98:99], 0x240000
	v_lshl_add_u64 v[8:9], v[4:5], 0, s[98:99]
	global_load_dword v130, v[8:9], off nt
	s_mov_b64 s[98:99], 0x249000
	v_lshl_add_u64 v[8:9], v[4:5], 0, s[98:99]
	global_load_dword v131, v[8:9], off nt
	s_mov_b64 s[98:99], 0x252000
	v_lshl_add_u64 v[8:9], v[4:5], 0, s[98:99]
	global_load_dword v132, v[8:9], off nt
	s_mov_b64 s[98:99], 0x25b000
	v_lshl_add_u64 v[8:9], v[4:5], 0, s[98:99]
	global_load_dword v133, v[8:9], off nt
	s_mov_b64 s[98:99], 0x264000
	v_lshl_add_u64 v[8:9], v[4:5], 0, s[98:99]
	global_load_dword v134, v[8:9], off nt
	s_mov_b64 s[98:99], 0x26d000
	v_lshl_add_u64 v[8:9], v[4:5], 0, s[98:99]
	global_load_dword v135, v[8:9], off nt
	s_mov_b64 s[98:99], 0x276000
	v_lshl_add_u64 v[8:9], v[4:5], 0, s[98:99]
	global_load_dword v136, v[8:9], off nt
	s_mov_b64 s[98:99], 0x27f000
	v_lshl_add_u64 v[8:9], v[4:5], 0, s[98:99]
	global_load_dword v137, v[8:9], off nt
	s_mov_b64 s[98:99], 0x288000
	v_lshl_add_u64 v[8:9], v[4:5], 0, s[98:99]
	global_load_dword v138, v[8:9], off nt
	s_mov_b64 s[98:99], 0x291000
	v_lshl_add_u64 v[8:9], v[4:5], 0, s[98:99]
	global_load_dword v139, v[8:9], off nt
	s_mov_b64 s[98:99], 0x29a000
	v_lshl_add_u64 v[8:9], v[4:5], 0, s[98:99]
	global_load_dword v140, v[8:9], off nt
	s_mov_b64 s[98:99], 0x2a3000
	v_lshl_add_u64 v[8:9], v[4:5], 0, s[98:99]
	global_load_dword v141, v[8:9], off nt
	s_mov_b64 s[98:99], 0x2ac000
	v_lshl_add_u64 v[8:9], v[4:5], 0, s[98:99]
	global_load_dword v142, v[8:9], off nt
	s_mov_b64 s[98:99], 0x2b5000
	v_lshl_add_u64 v[8:9], v[4:5], 0, s[98:99]
	global_load_dword v143, v[8:9], off nt
	s_mov_b64 s[98:99], 0x2be000
	v_lshl_add_u64 v[8:9], v[4:5], 0, s[98:99]
	global_load_dword v144, v[8:9], off nt
	s_mov_b64 s[98:99], 0x2c7000
	v_lshl_add_u64 v[8:9], v[4:5], 0, s[98:99]
	global_load_dword v145, v[8:9], off nt
	s_mov_b64 s[98:99], 0x2d0000
	v_lshl_add_u64 v[8:9], v[4:5], 0, s[98:99]
	global_load_dword v146, v[8:9], off nt
	s_mov_b64 s[98:99], 0x2d9000
	v_lshl_add_u64 v[8:9], v[4:5], 0, s[98:99]
	global_load_dword v147, v[8:9], off nt
	s_mov_b64 s[98:99], 0x2e2000
	v_lshl_add_u64 v[8:9], v[4:5], 0, s[98:99]
	global_load_dword v148, v[8:9], off nt
	s_mov_b64 s[98:99], 0x2eb000
	v_lshl_add_u64 v[8:9], v[4:5], 0, s[98:99]
	global_load_dword v149, v[8:9], off nt
	s_mov_b64 s[98:99], 0x2f4000
	v_lshl_add_u64 v[8:9], v[4:5], 0, s[98:99]
	global_load_dword v150, v[8:9], off nt
	s_mov_b64 s[98:99], 0x2fd000
	v_lshl_add_u64 v[8:9], v[4:5], 0, s[98:99]
	global_load_dword v151, v[8:9], off nt
	s_mov_b64 s[98:99], 0x306000
	v_lshl_add_u64 v[8:9], v[4:5], 0, s[98:99]
	global_load_dword v152, v[8:9], off nt
	s_mov_b64 s[98:99], 0x30f000
	v_lshl_add_u64 v[8:9], v[4:5], 0, s[98:99]
	global_load_dword v153, v[8:9], off nt
	s_mov_b64 s[98:99], 0x318000
	v_lshl_add_u64 v[8:9], v[4:5], 0, s[98:99]
	global_load_dword v154, v[8:9], off nt
	s_mov_b64 s[98:99], 0x321000
	v_lshl_add_u64 v[8:9], v[4:5], 0, s[98:99]
	global_load_dword v155, v[8:9], off nt
	s_mov_b64 s[98:99], 0x32a000
	v_lshl_add_u64 v[8:9], v[4:5], 0, s[98:99]
	global_load_dword v156, v[8:9], off nt
	s_mov_b64 s[98:99], 0x333000
	v_lshl_add_u64 v[8:9], v[4:5], 0, s[98:99]
	global_load_dword v157, v[8:9], off nt
	s_mov_b64 s[98:99], 0x33c000
	v_lshl_add_u64 v[8:9], v[4:5], 0, s[98:99]
	global_load_dword v158, v[8:9], off nt
	s_mov_b64 s[98:99], 0x345000
	v_lshl_add_u64 v[8:9], v[4:5], 0, s[98:99]
	global_load_dword v159, v[8:9], off nt
	s_mov_b64 s[98:99], 0x34e000
	v_lshl_add_u64 v[8:9], v[4:5], 0, s[98:99]
	global_load_dword v160, v[8:9], off nt
	s_mov_b64 s[98:99], 0x357000
	v_lshl_add_u64 v[8:9], v[4:5], 0, s[98:99]
	global_load_dword v161, v[8:9], off nt
	s_mov_b64 s[98:99], 0x360000
	v_lshl_add_u64 v[8:9], v[4:5], 0, s[98:99]
	global_load_dword v162, v[8:9], off nt
	s_mov_b64 s[98:99], 0x369000
	v_lshl_add_u64 v[8:9], v[4:5], 0, s[98:99]
	global_load_dword v163, v[8:9], off nt
	s_mov_b64 s[98:99], 0x372000
	v_lshl_add_u64 v[8:9], v[4:5], 0, s[98:99]
	global_load_dword v164, v[8:9], off nt
	s_mov_b64 s[98:99], 0x37b000
	v_lshl_add_u64 v[8:9], v[4:5], 0, s[98:99]
	global_load_dword v165, v[8:9], off nt
	s_mov_b64 s[98:99], 0x384000
	v_lshl_add_u64 v[8:9], v[4:5], 0, s[98:99]
	global_load_dword v166, v[8:9], off nt
	s_mov_b64 s[98:99], 0x38d000
	v_lshl_add_u64 v[8:9], v[4:5], 0, s[98:99]
	global_load_dword v167, v[8:9], off nt
	s_mov_b64 s[98:99], 0x396000
	v_lshl_add_u64 v[8:9], v[4:5], 0, s[98:99]
	global_load_dword v168, v[8:9], off nt
	s_mov_b64 s[98:99], 0x39f000
	v_lshl_add_u64 v[8:9], v[4:5], 0, s[98:99]
	global_load_dword v169, v[8:9], off nt
	s_mov_b64 s[98:99], 0x3a8000
	v_lshl_add_u64 v[8:9], v[4:5], 0, s[98:99]
	global_load_dword v170, v[8:9], off nt
	s_mov_b64 s[98:99], 0x3b1000
	v_lshl_add_u64 v[8:9], v[4:5], 0, s[98:99]
	global_load_dword v171, v[8:9], off nt
	s_mov_b64 s[98:99], 0x3ba000
	v_lshl_add_u64 v[8:9], v[4:5], 0, s[98:99]
	global_load_dword v172, v[8:9], off nt
	s_mov_b64 s[98:99], 0x3c3000
	v_lshl_add_u64 v[8:9], v[4:5], 0, s[98:99]
	global_load_dword v173, v[8:9], off nt
	s_mov_b64 s[98:99], 0x3cc000
	v_lshl_add_u64 v[8:9], v[4:5], 0, s[98:99]
	global_load_dword v174, v[8:9], off nt
	s_mov_b64 s[98:99], 0x3d5000
	v_lshl_add_u64 v[8:9], v[4:5], 0, s[98:99]
	global_load_dword v175, v[8:9], off nt
	s_mov_b64 s[98:99], 0x3de000
	v_lshl_add_u64 v[8:9], v[4:5], 0, s[98:99]
	global_load_dword v176, v[8:9], off nt
	s_mov_b64 s[98:99], 0x3e7000
	v_lshl_add_u64 v[8:9], v[4:5], 0, s[98:99]
	global_load_dword v177, v[8:9], off nt
	s_mov_b64 s[98:99], 0x3f0000
	v_lshl_add_u64 v[8:9], v[4:5], 0, s[98:99]
	global_load_dword v178, v[8:9], off nt
	s_mov_b64 s[98:99], 0x3f9000
	v_lshl_add_u64 v[8:9], v[4:5], 0, s[98:99]
	global_load_dword v179, v[8:9], off nt
	s_mov_b64 s[98:99], 0x402000
	v_lshl_add_u64 v[8:9], v[4:5], 0, s[98:99]
	global_load_dword v180, v[8:9], off nt
	s_mov_b64 s[98:99], 0x40b000
	v_lshl_add_u64 v[8:9], v[4:5], 0, s[98:99]
	global_load_dword v181, v[8:9], off nt
	s_mov_b64 s[98:99], 0x414000
	v_lshl_add_u64 v[8:9], v[4:5], 0, s[98:99]
	global_load_dword v182, v[8:9], off nt
	s_mov_b64 s[98:99], 0x41d000
	v_lshl_add_u64 v[8:9], v[4:5], 0, s[98:99]
	global_load_dword v183, v[8:9], off nt
	s_mov_b64 s[98:99], 0x426000
	v_lshl_add_u64 v[8:9], v[4:5], 0, s[98:99]
	global_load_dword v184, v[8:9], off nt
	s_mov_b64 s[98:99], 0x42f000
	v_lshl_add_u64 v[8:9], v[4:5], 0, s[98:99]
	global_load_dword v185, v[8:9], off nt
	s_mov_b64 s[98:99], 0x438000
	v_lshl_add_u64 v[8:9], v[4:5], 0, s[98:99]
	global_load_dword v186, v[8:9], off nt
	s_mov_b64 s[98:99], 0x441000
	v_lshl_add_u64 v[8:9], v[4:5], 0, s[98:99]
	global_load_dword v187, v[8:9], off nt
	s_mov_b64 s[98:99], 0x44a000
	v_lshl_add_u64 v[8:9], v[4:5], 0, s[98:99]
	global_load_dword v188, v[8:9], off nt
	s_mov_b64 s[98:99], 0x453000
	v_lshl_add_u64 v[8:9], v[4:5], 0, s[98:99]
	global_load_dword v189, v[8:9], off nt
	s_mov_b64 s[98:99], 0x45c000
	v_lshl_add_u64 v[8:9], v[4:5], 0, s[98:99]
	global_load_dword v190, v[8:9], off nt
	s_mov_b64 s[98:99], 0x465000
	v_lshl_add_u64 v[8:9], v[4:5], 0, s[98:99]
	global_load_dword v191, v[8:9], off nt
	s_mov_b64 s[98:99], 0x46e000
	v_lshl_add_u64 v[8:9], v[4:5], 0, s[98:99]
	global_load_dword v192, v[8:9], off nt
	s_mov_b64 s[98:99], 0x477000
	v_lshl_add_u64 v[8:9], v[4:5], 0, s[98:99]
	global_load_dword v193, v[8:9], off nt
	v_mov_b32_e32 v9, s4
	ds_read_b128 v[10:13], v9
	ds_read_b128 v[14:17], v9 offset:16
	ds_read_b128 v[18:21], v9 offset:32
	ds_read_b128 v[22:25], v9 offset:48
	ds_read_b128 v[26:29], v9 offset:4096
	s_waitcnt lgkmcnt(4)
	s_waitcnt vmcnt(63)
	v_fma_f32 v0, v66, v10, 0
	v_fmac_f32_e32 v0, v67, v11
	v_fmac_f32_e32 v0, v68, v12
	v_fmac_f32_e32 v0, v69, v13
	ds_read_b128 v[10:13], v9 offset:4112
	s_waitcnt lgkmcnt(1)
	v_fma_f32 v7, v66, v26, 0
	v_fmac_f32_e32 v7, v67, v27
	v_fmac_f32_e32 v7, v68, v28
	v_fmac_f32_e32 v7, v69, v29
	s_waitcnt lgkmcnt(0)
	v_fmac_f32_e32 v7, v70, v10
	v_fmac_f32_e32 v7, v71, v11
	ds_read_b128 v[30:33], v9 offset:8192
	v_fmac_f32_e32 v7, v72, v12
	v_fmac_f32_e32 v7, v73, v13
	ds_read_b128 v[10:13], v9 offset:4128
	ds_read_b128 v[26:29], v9 offset:8208
	s_waitcnt lgkmcnt(2)
	v_fma_f32 v8, v66, v30, 0
	v_fmac_f32_e32 v0, v70, v14
	v_fmac_f32_e32 v8, v67, v31
	v_fmac_f32_e32 v0, v71, v15
	s_waitcnt lgkmcnt(1)
	v_fmac_f32_e32 v7, v74, v10
	v_fmac_f32_e32 v8, v68, v32
	v_fmac_f32_e32 v0, v72, v16
	v_fmac_f32_e32 v7, v75, v11
	v_fmac_f32_e32 v8, v69, v33
	v_fmac_f32_e32 v0, v73, v17
	ds_read_b128 v[14:17], v9 offset:8224
	v_fmac_f32_e32 v7, v76, v12
	v_fmac_f32_e32 v7, v77, v13
	ds_read_b128 v[10:13], v9 offset:4144
	s_waitcnt lgkmcnt(2)
	v_fmac_f32_e32 v8, v70, v26
	v_fmac_f32_e32 v8, v71, v27
	v_fmac_f32_e32 v0, v74, v18
	v_fmac_f32_e32 v8, v72, v28
	v_fmac_f32_e32 v0, v75, v19
	v_fmac_f32_e32 v8, v73, v29
	v_fmac_f32_e32 v0, v76, v20
	v_fmac_f32_e32 v0, v77, v21
	ds_read_b128 v[18:21], v9 offset:8256
	s_waitcnt lgkmcnt(2)
	v_fmac_f32_e32 v8, v74, v14
	v_fmac_f32_e32 v8, v75, v15
	v_fmac_f32_e32 v8, v76, v16
	v_fmac_f32_e32 v8, v77, v17
	s_waitcnt lgkmcnt(1)
	v_fmac_f32_e32 v7, v78, v10
	ds_read_b128 v[14:17], v9 offset:8240
	v_fmac_f32_e32 v7, v79, v11
	v_fmac_f32_e32 v7, v80, v12
	v_fmac_f32_e32 v7, v81, v13
	ds_read_b128 v[10:13], v9 offset:64
	v_fmac_f32_e32 v0, v78, v22
	s_waitcnt lgkmcnt(1)
	v_fmac_f32_e32 v8, v78, v14
	v_fmac_f32_e32 v0, v79, v23
	v_fmac_f32_e32 v8, v79, v15
	v_fmac_f32_e32 v0, v80, v24
	v_fmac_f32_e32 v8, v80, v16
	v_fmac_f32_e32 v0, v81, v25
	v_fmac_f32_e32 v8, v81, v17
	ds_read_b128 v[14:17], v9 offset:4160
	s_waitcnt lgkmcnt(1)
	v_fmac_f32_e32 v0, v82, v10
	v_fmac_f32_e32 v0, v83, v11
	v_fmac_f32_e32 v0, v84, v12
	v_fmac_f32_e32 v0, v85, v13
	ds_read_b128 v[10:13], v9 offset:80
	s_waitcnt lgkmcnt(1)
	v_fmac_f32_e32 v7, v82, v14
	v_fmac_f32_e32 v7, v83, v15
	v_fmac_f32_e32 v7, v84, v16
	v_fmac_f32_e32 v7, v85, v17
	ds_read_b128 v[14:17], v9 offset:4176
	s_waitcnt lgkmcnt(1)
	v_fmac_f32_e32 v0, v86, v10
	v_fmac_f32_e32 v0, v87, v11
	v_fmac_f32_e32 v0, v88, v12
	v_fmac_f32_e32 v0, v89, v13
	ds_read_b128 v[10:13], v9 offset:96
	s_waitcnt lgkmcnt(1)
	v_fmac_f32_e32 v7, v86, v14
	v_fmac_f32_e32 v7, v87, v15
	v_fmac_f32_e32 v7, v88, v16
	v_fmac_f32_e32 v7, v89, v17
	ds_read_b128 v[14:17], v9 offset:4192
	s_waitcnt lgkmcnt(1)
	v_fmac_f32_e32 v0, v90, v10
	v_fmac_f32_e32 v0, v91, v11
	v_fmac_f32_e32 v0, v92, v12
	v_fmac_f32_e32 v0, v93, v13
	ds_read_b128 v[10:13], v9 offset:112
	s_waitcnt lgkmcnt(1)
	v_fmac_f32_e32 v7, v90, v14
	v_fmac_f32_e32 v7, v91, v15
	v_fmac_f32_e32 v7, v92, v16
	v_fmac_f32_e32 v7, v93, v17
	ds_read_b128 v[14:17], v9 offset:4208
	s_waitcnt lgkmcnt(1)
	v_fmac_f32_e32 v0, v94, v10
	v_fmac_f32_e32 v0, v95, v11
	v_fmac_f32_e32 v8, v82, v18
	v_fmac_f32_e32 v8, v83, v19
	s_nop 0
	v_fmac_f32_e32 v8, v84, v20
	v_fmac_f32_e32 v0, v96, v12
	v_fmac_f32_e32 v8, v85, v21
	v_fmac_f32_e32 v0, v97, v13
	ds_read_b128 v[10:13], v9 offset:128
	s_waitcnt lgkmcnt(1)
	v_fmac_f32_e32 v7, v94, v14
	v_fmac_f32_e32 v7, v95, v15
	v_fmac_f32_e32 v7, v96, v16
	v_fmac_f32_e32 v7, v97, v17
	ds_read_b128 v[14:17], v9 offset:4224
	s_waitcnt lgkmcnt(1)
	v_fmac_f32_e32 v0, v98, v10
	v_fmac_f32_e32 v0, v99, v11
	v_fmac_f32_e32 v0, v100, v12
	v_fmac_f32_e32 v0, v101, v13
	ds_read_b128 v[10:13], v9 offset:144
	s_waitcnt lgkmcnt(1)
	v_fmac_f32_e32 v7, v98, v14
	v_fmac_f32_e32 v7, v99, v15
	v_fmac_f32_e32 v7, v100, v16
	v_fmac_f32_e32 v7, v101, v17
	ds_read_b128 v[14:17], v9 offset:4240
	s_waitcnt lgkmcnt(1)
	v_fmac_f32_e32 v0, v102, v10
	v_fmac_f32_e32 v0, v103, v11
	v_fmac_f32_e32 v0, v104, v12
	v_fmac_f32_e32 v0, v105, v13
	ds_read_b128 v[10:13], v9 offset:160
	s_waitcnt lgkmcnt(1)
	v_fmac_f32_e32 v7, v102, v14
	v_fmac_f32_e32 v7, v103, v15
	v_fmac_f32_e32 v7, v104, v16
	v_fmac_f32_e32 v7, v105, v17
	ds_read_b128 v[14:17], v9 offset:4256
	s_waitcnt lgkmcnt(1)
	v_fmac_f32_e32 v0, v106, v10
	v_fmac_f32_e32 v0, v107, v11
	v_fmac_f32_e32 v0, v108, v12
	v_fmac_f32_e32 v0, v109, v13
	ds_read_b128 v[10:13], v9 offset:176
	s_waitcnt lgkmcnt(1)
	v_fmac_f32_e32 v7, v106, v14
	v_fmac_f32_e32 v7, v107, v15
	v_fmac_f32_e32 v7, v108, v16
	v_fmac_f32_e32 v7, v109, v17
	ds_read_b128 v[14:17], v9 offset:4272
	s_waitcnt lgkmcnt(1)
	v_fmac_f32_e32 v0, v110, v10
	v_fmac_f32_e32 v0, v111, v11
	v_fmac_f32_e32 v0, v112, v12
	v_fmac_f32_e32 v0, v113, v13
	ds_read_b128 v[10:13], v9 offset:192
	ds_read_b128 v[18:21], v9 offset:8272
	s_waitcnt lgkmcnt(2)
	v_fmac_f32_e32 v7, v110, v14
	v_fmac_f32_e32 v7, v111, v15
	v_fmac_f32_e32 v7, v112, v16
	v_fmac_f32_e32 v7, v113, v17
	ds_read_b128 v[14:17], v9 offset:4288
	s_waitcnt lgkmcnt(2)
	v_fmac_f32_e32 v0, v114, v10
	v_fmac_f32_e32 v0, v115, v11
	s_waitcnt lgkmcnt(1)
	v_fmac_f32_e32 v8, v86, v18
	v_fmac_f32_e32 v0, v116, v12
	v_fmac_f32_e32 v8, v87, v19
	v_fmac_f32_e32 v0, v117, v13
	ds_read_b128 v[10:13], v9 offset:208
	v_fmac_f32_e32 v8, v88, v20
	v_fmac_f32_e32 v8, v89, v21
	ds_read_b128 v[18:21], v9 offset:8288
	s_waitcnt lgkmcnt(2)
	v_fmac_f32_e32 v7, v114, v14
	v_fmac_f32_e32 v7, v115, v15
	v_fmac_f32_e32 v7, v116, v16
	v_fmac_f32_e32 v7, v117, v17
	ds_read_b128 v[14:17], v9 offset:4304
	s_waitcnt lgkmcnt(2)
	v_fmac_f32_e32 v0, v118, v10
	v_fmac_f32_e32 v0, v119, v11
	s_waitcnt lgkmcnt(1)
	v_fmac_f32_e32 v8, v90, v18
	v_fmac_f32_e32 v0, v120, v12
	v_fmac_f32_e32 v8, v91, v19
	v_fmac_f32_e32 v0, v121, v13
	ds_read_b128 v[10:13], v9 offset:224
	v_fmac_f32_e32 v8, v92, v20
	v_fmac_f32_e32 v8, v93, v21
	ds_read_b128 v[18:21], v9 offset:8304
	s_waitcnt lgkmcnt(2)
	v_fmac_f32_e32 v7, v118, v14
	v_fmac_f32_e32 v7, v119, v15
	v_fmac_f32_e32 v7, v120, v16
	v_fmac_f32_e32 v7, v121, v17
	ds_read_b128 v[14:17], v9 offset:4320
	s_waitcnt lgkmcnt(2)
	v_fmac_f32_e32 v0, v122, v10
	v_fmac_f32_e32 v0, v123, v11
	s_waitcnt lgkmcnt(1)
	v_fmac_f32_e32 v8, v94, v18
	v_fmac_f32_e32 v0, v124, v12
	v_fmac_f32_e32 v8, v95, v19
	v_fmac_f32_e32 v0, v125, v13
	ds_read_b128 v[10:13], v9 offset:240
	v_fmac_f32_e32 v8, v96, v20
	v_fmac_f32_e32 v8, v97, v21
	ds_read_b128 v[18:21], v9 offset:8320
	s_waitcnt lgkmcnt(2)
	v_fmac_f32_e32 v7, v122, v14
	v_fmac_f32_e32 v7, v123, v15
	v_fmac_f32_e32 v7, v124, v16
	v_fmac_f32_e32 v7, v125, v17
	ds_read_b128 v[14:17], v9 offset:4336
	s_waitcnt lgkmcnt(2)
	v_fmac_f32_e32 v0, v126, v10
	v_fmac_f32_e32 v0, v127, v11
	s_waitcnt lgkmcnt(1)
	v_fmac_f32_e32 v8, v98, v18
	v_fmac_f32_e32 v8, v99, v19
	s_nop 0
	v_fmac_f32_e32 v8, v100, v20
	v_fmac_f32_e32 v8, v101, v21
	ds_read_b128 v[18:21], v9 offset:8336
	s_waitcnt lgkmcnt(0)
	v_fmac_f32_e32 v8, v102, v18
	v_fmac_f32_e32 v8, v103, v19
	s_nop 0
	v_fmac_f32_e32 v8, v104, v20
	v_fmac_f32_e32 v8, v105, v21
	ds_read_b128 v[18:21], v9 offset:8352
	s_waitcnt lgkmcnt(0)
	v_fmac_f32_e32 v8, v106, v18
	v_fmac_f32_e32 v8, v107, v19
	s_nop 0
	v_fmac_f32_e32 v8, v108, v20
	v_fmac_f32_e32 v8, v109, v21
	ds_read_b128 v[18:21], v9 offset:8368
	s_waitcnt lgkmcnt(0)
	v_fmac_f32_e32 v8, v110, v18
	v_fmac_f32_e32 v8, v111, v19
	s_nop 0
	v_fmac_f32_e32 v8, v112, v20
	v_fmac_f32_e32 v8, v113, v21
	ds_read_b128 v[18:21], v9 offset:8384
	s_waitcnt lgkmcnt(0)
	v_fmac_f32_e32 v8, v114, v18
	v_fmac_f32_e32 v8, v115, v19
	s_nop 0
	v_fmac_f32_e32 v8, v116, v20
	v_fmac_f32_e32 v8, v117, v21
	ds_read_b128 v[18:21], v9 offset:8400
	s_waitcnt lgkmcnt(0)
	v_fmac_f32_e32 v8, v118, v18
	v_fmac_f32_e32 v8, v119, v19
	s_nop 0
	v_fmac_f32_e32 v8, v120, v20
	v_fmac_f32_e32 v8, v121, v21
	ds_read_b128 v[18:21], v9 offset:8416
	s_waitcnt lgkmcnt(0)
	v_fmac_f32_e32 v8, v122, v18
	v_fmac_f32_e32 v8, v123, v19
	v_fmac_f32_e32 v8, v124, v20
	v_fmac_f32_e32 v8, v125, v21
	ds_read_b128 v[18:21], v9 offset:8432
	v_fmac_f32_e32 v7, v126, v14
	s_waitcnt lgkmcnt(0)
	v_fmac_f32_e32 v8, v126, v18
	v_fmac_f32_e32 v7, v127, v15
	s_nop 0
	v_fmac_f32_e32 v8, v127, v19
	v_fmac_f32_e32 v0, v128, v12
	v_fmac_f32_e32 v7, v128, v16
	v_fmac_f32_e32 v8, v128, v20
	v_fmac_f32_e32 v0, v129, v13
	v_fmac_f32_e32 v7, v129, v17
	v_fmac_f32_e32 v8, v129, v21
	ds_read_b128 v[10:13], v9 offset:256
	ds_read_b128 v[14:17], v9 offset:4352
	ds_read_b128 v[18:21], v9 offset:8448
	s_waitcnt lgkmcnt(2)
	v_fmac_f32_e32 v0, v130, v10
	s_waitcnt vmcnt(62)
	v_fmac_f32_e32 v0, v131, v11
	s_waitcnt vmcnt(61)
	v_fmac_f32_e32 v0, v132, v12
	s_waitcnt vmcnt(60)
	v_fmac_f32_e32 v0, v133, v13
	ds_read_b128 v[10:13], v9 offset:272
	s_waitcnt lgkmcnt(2)
	v_fmac_f32_e32 v7, v130, v14
	v_fmac_f32_e32 v7, v131, v15
	v_fmac_f32_e32 v7, v132, v16
	v_fmac_f32_e32 v7, v133, v17
	ds_read_b128 v[14:17], v9 offset:4368
	s_waitcnt lgkmcnt(1)
	s_waitcnt vmcnt(59)
	v_fmac_f32_e32 v0, v134, v10
	s_waitcnt vmcnt(58)
	v_fmac_f32_e32 v0, v135, v11
	s_waitcnt vmcnt(57)
	v_fmac_f32_e32 v0, v136, v12
	s_waitcnt vmcnt(56)
	v_fmac_f32_e32 v0, v137, v13
	ds_read_b128 v[10:13], v9 offset:288
	s_waitcnt lgkmcnt(1)
	v_fmac_f32_e32 v7, v134, v14
	v_fmac_f32_e32 v7, v135, v15
	v_fmac_f32_e32 v7, v136, v16
	v_fmac_f32_e32 v7, v137, v17
	ds_read_b128 v[14:17], v9 offset:4384
	s_waitcnt lgkmcnt(1)
	s_waitcnt vmcnt(55)
	v_fmac_f32_e32 v0, v138, v10
	s_waitcnt vmcnt(54)
	v_fmac_f32_e32 v0, v139, v11
	s_waitcnt vmcnt(53)
	v_fmac_f32_e32 v0, v140, v12
	s_waitcnt vmcnt(52)
	v_fmac_f32_e32 v0, v141, v13
	ds_read_b128 v[10:13], v9 offset:304
	s_waitcnt lgkmcnt(1)
	v_fmac_f32_e32 v7, v138, v14
	v_fmac_f32_e32 v7, v139, v15
	v_fmac_f32_e32 v7, v140, v16
	v_fmac_f32_e32 v7, v141, v17
	ds_read_b128 v[14:17], v9 offset:4400
	s_waitcnt lgkmcnt(1)
	s_waitcnt vmcnt(51)
	v_fmac_f32_e32 v0, v142, v10
	s_waitcnt vmcnt(50)
	v_fmac_f32_e32 v0, v143, v11
	s_waitcnt vmcnt(49)
	v_fmac_f32_e32 v0, v144, v12
	s_waitcnt vmcnt(48)
	v_fmac_f32_e32 v0, v145, v13
	ds_read_b128 v[10:13], v9 offset:320
	v_fmac_f32_e32 v8, v130, v18
	v_fmac_f32_e32 v8, v131, v19
	s_waitcnt lgkmcnt(1)
	v_fmac_f32_e32 v7, v142, v14
	v_fmac_f32_e32 v8, v132, v20
	v_fmac_f32_e32 v7, v143, v15
	v_fmac_f32_e32 v8, v133, v21
	ds_read_b128 v[18:21], v9 offset:8464
	v_fmac_f32_e32 v7, v144, v16
	v_fmac_f32_e32 v7, v145, v17
	ds_read_b128 v[14:17], v9 offset:4416
	s_waitcnt lgkmcnt(2)
	s_waitcnt vmcnt(47)
	v_fmac_f32_e32 v0, v146, v10
	s_waitcnt vmcnt(46)
	v_fmac_f32_e32 v0, v147, v11
	s_waitcnt vmcnt(45)
	v_fmac_f32_e32 v0, v148, v12
	s_waitcnt vmcnt(44)
	v_fmac_f32_e32 v0, v149, v13
	ds_read_b128 v[10:13], v9 offset:336
	s_waitcnt lgkmcnt(2)
	v_fmac_f32_e32 v8, v134, v18
	v_fmac_f32_e32 v8, v135, v19
	s_waitcnt lgkmcnt(1)
	v_fmac_f32_e32 v7, v146, v14
	v_fmac_f32_e32 v8, v136, v20
	v_fmac_f32_e32 v7, v147, v15
	v_fmac_f32_e32 v8, v137, v21
	ds_read_b128 v[18:21], v9 offset:8480
	v_fmac_f32_e32 v7, v148, v16
	v_fmac_f32_e32 v7, v149, v17
	ds_read_b128 v[14:17], v9 offset:4432
	s_waitcnt lgkmcnt(2)
	s_waitcnt vmcnt(43)
	v_fmac_f32_e32 v0, v150, v10
	s_waitcnt vmcnt(42)
	v_fmac_f32_e32 v0, v151, v11
	s_waitcnt vmcnt(41)
	v_fmac_f32_e32 v0, v152, v12
	s_waitcnt vmcnt(40)
	v_fmac_f32_e32 v0, v153, v13
	ds_read_b128 v[10:13], v9 offset:352
	s_waitcnt lgkmcnt(2)
	v_fmac_f32_e32 v8, v138, v18
	v_fmac_f32_e32 v8, v139, v19
	s_waitcnt lgkmcnt(1)
	v_fmac_f32_e32 v7, v150, v14
	v_fmac_f32_e32 v8, v140, v20
	v_fmac_f32_e32 v7, v151, v15
	v_fmac_f32_e32 v8, v141, v21
	ds_read_b128 v[18:21], v9 offset:8496
	v_fmac_f32_e32 v7, v152, v16
	v_fmac_f32_e32 v7, v153, v17
	ds_read_b128 v[14:17], v9 offset:4448
	s_waitcnt lgkmcnt(2)
	s_waitcnt vmcnt(39)
	v_fmac_f32_e32 v0, v154, v10
	s_waitcnt vmcnt(38)
	v_fmac_f32_e32 v0, v155, v11
	s_waitcnt vmcnt(37)
	v_fmac_f32_e32 v0, v156, v12
	s_waitcnt vmcnt(36)
	v_fmac_f32_e32 v0, v157, v13
	ds_read_b128 v[10:13], v9 offset:368
	s_waitcnt lgkmcnt(2)
	v_fmac_f32_e32 v8, v142, v18
	v_fmac_f32_e32 v8, v143, v19
	s_waitcnt lgkmcnt(1)
	v_fmac_f32_e32 v7, v154, v14
	v_fmac_f32_e32 v8, v144, v20
	v_fmac_f32_e32 v7, v155, v15
	v_fmac_f32_e32 v8, v145, v21
	ds_read_b128 v[18:21], v9 offset:8512
	v_fmac_f32_e32 v7, v156, v16
	v_fmac_f32_e32 v7, v157, v17
	ds_read_b128 v[14:17], v9 offset:4464
	s_waitcnt lgkmcnt(2)
	s_waitcnt vmcnt(35)
	v_fmac_f32_e32 v0, v158, v10
	s_waitcnt vmcnt(34)
	v_fmac_f32_e32 v0, v159, v11
	s_waitcnt lgkmcnt(1)
	v_fmac_f32_e32 v8, v146, v18
	v_fmac_f32_e32 v8, v147, v19
	v_fmac_f32_e32 v8, v148, v20
	s_nop 0
	v_fmac_f32_e32 v8, v149, v21
	ds_read_b128 v[18:21], v9 offset:8528
	s_waitcnt vmcnt(33)
	v_fmac_f32_e32 v0, v160, v12
	s_waitcnt vmcnt(32)
	v_fmac_f32_e32 v0, v161, v13
	s_waitcnt lgkmcnt(0)
	v_fmac_f32_e32 v8, v150, v18
	v_fmac_f32_e32 v7, v158, v14
	v_fmac_f32_e32 v8, v151, v19
	s_nop 0
	v_fmac_f32_e32 v8, v152, v20
	v_fmac_f32_e32 v7, v159, v15
	v_fmac_f32_e32 v8, v153, v21
	ds_read_b128 v[18:21], v9 offset:8544
	s_waitcnt lgkmcnt(0)
	v_fmac_f32_e32 v8, v154, v18
	v_fmac_f32_e32 v8, v155, v19
	s_nop 0
	v_fmac_f32_e32 v8, v156, v20
	v_fmac_f32_e32 v8, v157, v21
	ds_read_b128 v[18:21], v9 offset:8560
	v_fmac_f32_e32 v7, v160, v16
	s_nop 0
	v_fmac_f32_e32 v7, v161, v17
	s_waitcnt lgkmcnt(0)
	v_fmac_f32_e32 v8, v158, v18
	v_fmac_f32_e32 v8, v159, v19
	s_nop 0
	v_fmac_f32_e32 v8, v160, v20
	v_fmac_f32_e32 v8, v161, v21
	ds_read_b128 v[46:49], v9 offset:4480
	ds_read_b128 v[42:45], v9 offset:384
	ds_read_b128 v[50:53], v9 offset:8576
	s_waitcnt lgkmcnt(2)
	s_waitcnt vmcnt(31)
	v_fmac_f32_e32 v7, v162, v46
	s_waitcnt vmcnt(30)
	v_fmac_f32_e32 v7, v163, v47
	s_waitcnt vmcnt(29)
	v_fmac_f32_e32 v7, v164, v48
	s_waitcnt lgkmcnt(1)
	v_fmac_f32_e32 v0, v162, v42
	s_waitcnt vmcnt(28)
	v_fmac_f32_e32 v7, v165, v49
	ds_read_b128 v[46:49], v9 offset:8592
	s_waitcnt lgkmcnt(1)
	v_fmac_f32_e32 v8, v162, v50
	v_fmac_f32_e32 v0, v163, v43
	v_fmac_f32_e32 v8, v163, v51
	v_fmac_f32_e32 v0, v164, v44
	v_fmac_f32_e32 v8, v164, v52
	v_fmac_f32_e32 v0, v165, v45
	v_fmac_f32_e32 v8, v165, v53
	ds_read_b128 v[38:41], v9 offset:400
	ds_read_b128 v[42:45], v9 offset:4496
	s_waitcnt lgkmcnt(2)
	s_waitcnt vmcnt(27)
	v_fmac_f32_e32 v8, v166, v46
	s_waitcnt vmcnt(26)
	v_fmac_f32_e32 v8, v167, v47
	s_waitcnt vmcnt(25)
	v_fmac_f32_e32 v8, v168, v48
	s_waitcnt lgkmcnt(1)
	v_fmac_f32_e32 v0, v166, v38
	s_waitcnt lgkmcnt(0)
	v_fmac_f32_e32 v7, v166, v42
	v_fmac_f32_e32 v0, v167, v39
	v_fmac_f32_e32 v7, v167, v43
	v_fmac_f32_e32 v0, v168, v40
	v_fmac_f32_e32 v7, v168, v44
	s_waitcnt vmcnt(24)
	v_fmac_f32_e32 v0, v169, v41
	v_fmac_f32_e32 v7, v169, v45
	ds_read_b128 v[38:41], v9 offset:416
	ds_read_b128 v[42:45], v9 offset:4512
	v_fmac_f32_e32 v8, v169, v49
	ds_read_b128 v[46:49], v9 offset:8608
	s_waitcnt lgkmcnt(2)
	s_waitcnt vmcnt(23)
	v_fmac_f32_e32 v0, v170, v38
	s_waitcnt lgkmcnt(1)
	v_fmac_f32_e32 v7, v170, v42
	s_waitcnt vmcnt(22)
	v_fmac_f32_e32 v7, v171, v43
	s_waitcnt vmcnt(21)
	v_fmac_f32_e32 v7, v172, v44
	v_fmac_f32_e32 v0, v171, v39
	s_waitcnt vmcnt(20)
	v_fmac_f32_e32 v7, v173, v45
	ds_read_b128 v[42:45], v9 offset:8624
	s_waitcnt lgkmcnt(1)
	v_fmac_f32_e32 v8, v170, v46
	v_fmac_f32_e32 v8, v171, v47
	v_fmac_f32_e32 v0, v172, v40
	ds_read_b128 v[24:27], v9 offset:432
	v_fmac_f32_e32 v0, v173, v41
	ds_read_b128 v[38:41], v9 offset:4528
	v_fmac_f32_e32 v8, v172, v48
	v_fmac_f32_e32 v8, v173, v49
	s_waitcnt lgkmcnt(1)
	s_waitcnt vmcnt(19)
	v_fmac_f32_e32 v0, v174, v24
	v_fmac_f32_e32 v8, v174, v42
	s_waitcnt lgkmcnt(0)
	v_fmac_f32_e32 v7, v174, v38
	s_waitcnt vmcnt(18)
	v_fmac_f32_e32 v0, v175, v25
	v_fmac_f32_e32 v7, v175, v39
	v_fmac_f32_e32 v8, v175, v43
	s_waitcnt vmcnt(17)
	v_fmac_f32_e32 v0, v176, v26
	v_fmac_f32_e32 v7, v176, v40
	v_fmac_f32_e32 v8, v176, v44
	s_waitcnt vmcnt(16)
	v_fmac_f32_e32 v0, v177, v27
	ds_read_b128 v[24:27], v9 offset:448
	v_fmac_f32_e32 v7, v177, v41
	v_fmac_f32_e32 v8, v177, v45
	ds_read_b128 v[38:41], v9 offset:4544
	ds_read_b128 v[42:45], v9 offset:8640
	s_waitcnt lgkmcnt(2)
	s_waitcnt vmcnt(15)
	v_fmac_f32_e32 v0, v178, v24
	s_waitcnt vmcnt(14)
	v_fmac_f32_e32 v0, v179, v25
	s_waitcnt vmcnt(13)
	v_fmac_f32_e32 v0, v180, v26
	s_waitcnt lgkmcnt(1)
	v_fmac_f32_e32 v7, v178, v38
	s_waitcnt lgkmcnt(0)
	v_fmac_f32_e32 v8, v178, v42
	v_fmac_f32_e32 v7, v179, v39
	v_fmac_f32_e32 v8, v179, v43
	v_fmac_f32_e32 v7, v180, v40
	v_fmac_f32_e32 v8, v180, v44
	s_waitcnt vmcnt(12)
	v_fmac_f32_e32 v0, v181, v27
	ds_read_b128 v[24:27], v9 offset:464
	ds_read_b128 v[28:31], v9 offset:4560
	ds_read_b128 v[32:35], v9 offset:8656
	v_fmac_f32_e32 v7, v181, v41
	v_fmac_f32_e32 v8, v181, v45
	s_waitcnt lgkmcnt(2)
	s_waitcnt vmcnt(11)
	v_fmac_f32_e32 v0, v182, v24
	s_waitcnt lgkmcnt(1)
	v_fmac_f32_e32 v7, v182, v28
	s_waitcnt lgkmcnt(0)
	v_fmac_f32_e32 v8, v182, v32
	s_waitcnt vmcnt(10)
	v_fmac_f32_e32 v0, v183, v25
	v_fmac_f32_e32 v7, v183, v29
	v_fmac_f32_e32 v8, v183, v33
	s_waitcnt vmcnt(9)
	v_fmac_f32_e32 v0, v184, v26
	v_fmac_f32_e32 v7, v184, v30
	v_fmac_f32_e32 v8, v184, v34
	s_waitcnt vmcnt(8)
	v_fmac_f32_e32 v0, v185, v27
	v_fmac_f32_e32 v7, v185, v31
	v_fmac_f32_e32 v8, v185, v35
	ds_read_b128 v[24:27], v9 offset:480
	ds_read_b128 v[28:31], v9 offset:4576
	ds_read_b128 v[32:35], v9 offset:8672
	s_waitcnt lgkmcnt(2)
	s_waitcnt vmcnt(7)
	v_fmac_f32_e32 v0, v186, v24
	s_waitcnt lgkmcnt(1)
	v_fmac_f32_e32 v7, v186, v28
	s_waitcnt lgkmcnt(0)
	v_fmac_f32_e32 v8, v186, v32
	s_waitcnt vmcnt(6)
	v_fmac_f32_e32 v0, v187, v25
	v_fmac_f32_e32 v7, v187, v29
	v_fmac_f32_e32 v8, v187, v33
	s_waitcnt vmcnt(5)
	v_fmac_f32_e32 v0, v188, v26
	v_fmac_f32_e32 v7, v188, v30
	v_fmac_f32_e32 v8, v188, v34
	ds_read_b128 v[14:17], v9 offset:496
	ds_read_b128 v[18:21], v9 offset:4592
	s_waitcnt vmcnt(4)
	v_fmac_f32_e32 v0, v189, v27
	v_fmac_f32_e32 v7, v189, v31
	v_fmac_f32_e32 v8, v189, v35
	ds_read_b128 v[22:25], v9 offset:8688
	s_waitcnt lgkmcnt(2)
	s_waitcnt vmcnt(3)
	v_fmac_f32_e32 v0, v190, v14
	s_waitcnt lgkmcnt(1)
	v_fmac_f32_e32 v7, v190, v18
	s_waitcnt vmcnt(2)
	v_fmac_f32_e32 v0, v191, v15
	v_fmac_f32_e32 v7, v191, v19
	s_waitcnt lgkmcnt(0)
	v_fmac_f32_e32 v8, v190, v22
	v_fmac_f32_e32 v8, v191, v23
	s_waitcnt vmcnt(1)
	v_fmac_f32_e32 v0, v192, v16
	v_fmac_f32_e32 v7, v192, v20
	v_fmac_f32_e32 v8, v192, v24
	s_waitcnt vmcnt(0)
	v_fmac_f32_e32 v0, v193, v17
	v_fmac_f32_e32 v7, v193, v21
	v_fmac_f32_e32 v8, v193, v25
	ds_write2st64_b32 v6, v0, v7 offset0:48 offset1:49
	ds_write_b32 v6, v8 offset:12800
	s_waitcnt lgkmcnt(0)
	s_barrier
	s_and_saveexec_b64 s[4:5], s[2:3]
	s_cbranch_execz .LBB0_1145
	s_mul_i32 s2, s6, 0x2400
	v_lshlrev_b32_e32 v0, 2, v3
	v_lshlrev_b32_e32 v6, 8, v2
	s_add_i32 s2, s2, s7
	v_add3_u32 v8, 0, v0, v6
	v_add_u32_e32 v6, s2, v3
	v_mov_b32_e32 v4, s10
	v_mov_b32_e32 v5, s11
	v_ashrrev_i32_e32 v7, 31, v6
	v_lshl_add_u64 v[4:5], v[6:7], 2, v[4:5]
	global_load_dword v3, v[4:5], off
	ds_read2st64_b32 v[4:5], v8 offset0:48 offset1:51
	s_waitcnt vmcnt(0) lgkmcnt(0)
	v_add_f32_e32 v3, v3, v4
	v_add_f32_e32 v3, v3, v5
	ds_read2st64_b32 v[4:5], v8 offset0:54 offset1:57
	s_waitcnt lgkmcnt(0)
	v_add_f32_e32 v3, v3, v4
	v_add_f32_e32 v3, v3, v5
	ds_read2st64_b32 v[4:5], v8 offset0:60 offset1:63
	s_waitcnt lgkmcnt(0)
	v_add_f32_e32 v3, v3, v4
	v_add_f32_e32 v3, v3, v5
	ds_read2st64_b32 v[4:5], v8 offset0:66 offset1:69
	s_waitcnt lgkmcnt(0)
	v_add_f32_e32 v3, v3, v4
	v_add_f32_e32 v6, v3, v5
	v_mad_u64_u32 v[2:3], s[2:3], s6, 3, v[2:3]
	v_mov_b64_e32 v[4:5], s[68:69]
	v_mad_i64_i32 v[2:3], s[2:3], v2, s87, v[4:5]
	v_lshl_add_u64 v[2:3], v[2:3], 0, s[80:81]
	v_lshl_add_u64 v[2:3], v[2:3], 0, v[0:1]
	global_store_dword v[2:3], v6, off

.LBB0_1199:
	s_or_b64 exec, exec, s[4:5]
	s_waitcnt lgkmcnt(0)
	s_barrier
	s_load_dwordx4 s[8:11], s[0:1], 0x20
	s_lshl_b32 s4, s13, 7
	s_mul_i32 s5, s13, 0x480000
	s_mul_hi_i32 s4, s4, 0x9000
	v_and_b32_e32 v3, 63, v4
	s_waitcnt lgkmcnt(0)
	s_add_u32 s5, s8, s5
	s_addc_u32 s14, s9, s4
	s_lshl_b32 s4, s13, 9
	s_mulk_i32 s13, 0x300
	s_add_i32 s6, s13, 0
	v_lshl_add_u32 v6, v3, 2, s6
	s_movk_i32 s6, 0xc0
	v_cmp_gt_u32_e32 vcc, 36, v3
	v_cmp_gt_i32_e64 s[6:7], s6, v4
	s_ashr_i32 s8, s12, 8
	s_add_i32 s4, s4, 0
	s_and_b64 s[6:7], s[6:7], vcc
	s_and_b32 s9, s12, 0xff
	s_mul_i32 s13, s8, 0x2400000
	s_mul_i32 s9, s9, 36
	s_mul_hi_i32 s12, s8, 0x2400000
	s_add_u32 s5, s5, s13
	s_addc_u32 s13, s14, s12
	s_lshl_b32 s80, s9, 2
	v_min_u32_e32 v0, 35, v3
	s_add_u32 s12, s5, s80
	s_addc_u32 s13, s13, 0
	v_lshlrev_b32_e32 v0, 2, v0
	v_lshl_add_u64 v[4:5], s[12:13], 0, v[0:1]
	global_load_dword v66, v[4:5], off nt
	s_mov_b64 s[98:99], 0x9000
	v_lshl_add_u64 v[8:9], v[4:5], 0, s[98:99]
	global_load_dword v67, v[8:9], off nt
	s_mov_b64 s[98:99], 0x12000
	v_lshl_add_u64 v[8:9], v[4:5], 0, s[98:99]
	global_load_dword v68, v[8:9], off nt
	s_mov_b64 s[98:99], 0x1b000
	v_lshl_add_u64 v[8:9], v[4:5], 0, s[98:99]
	global_load_dword v69, v[8:9], off nt
	s_mov_b64 s[98:99], 0x24000
	v_lshl_add_u64 v[8:9], v[4:5], 0, s[98:99]
	global_load_dword v70, v[8:9], off nt
	s_mov_b64 s[98:99], 0x2d000
	v_lshl_add_u64 v[8:9], v[4:5], 0, s[98:99]
	global_load_dword v71, v[8:9], off nt
	s_mov_b64 s[98:99], 0x36000
	v_lshl_add_u64 v[8:9], v[4:5], 0, s[98:99]
	global_load_dword v72, v[8:9], off nt
	s_mov_b64 s[98:99], 0x3f000
	v_lshl_add_u64 v[8:9], v[4:5], 0, s[98:99]
	global_load_dword v73, v[8:9], off nt
	s_mov_b64 s[98:99], 0x48000
	v_lshl_add_u64 v[8:9], v[4:5], 0, s[98:99]
	global_load_dword v74, v[8:9], off nt
	s_mov_b64 s[98:99], 0x51000
	v_lshl_add_u64 v[8:9], v[4:5], 0, s[98:99]
	global_load_dword v75, v[8:9], off nt
	s_mov_b64 s[98:99], 0x5a000
	v_lshl_add_u64 v[8:9], v[4:5], 0, s[98:99]
	global_load_dword v76, v[8:9], off nt
	s_mov_b64 s[98:99], 0x63000
	v_lshl_add_u64 v[8:9], v[4:5], 0, s[98:99]
	global_load_dword v77, v[8:9], off nt
	s_mov_b64 s[98:99], 0x6c000
	v_lshl_add_u64 v[8:9], v[4:5], 0, s[98:99]
	global_load_dword v78, v[8:9], off nt
	s_mov_b64 s[98:99], 0x75000
	v_lshl_add_u64 v[8:9], v[4:5], 0, s[98:99]
	global_load_dword v79, v[8:9], off nt
	s_mov_b64 s[98:99], 0x7e000
	v_lshl_add_u64 v[8:9], v[4:5], 0, s[98:99]
	global_load_dword v80, v[8:9], off nt
	s_mov_b64 s[98:99], 0x87000
	v_lshl_add_u64 v[8:9], v[4:5], 0, s[98:99]
	global_load_dword v81, v[8:9], off nt
	s_mov_b64 s[98:99], 0x90000
	v_lshl_add_u64 v[8:9], v[4:5], 0, s[98:99]
	global_load_dword v82, v[8:9], off nt
	s_mov_b64 s[98:99], 0x99000
	v_lshl_add_u64 v[8:9], v[4:5], 0, s[98:99]
	global_load_dword v83, v[8:9], off nt
	s_mov_b64 s[98:99], 0xa2000
	v_lshl_add_u64 v[8:9], v[4:5], 0, s[98:99]
	global_load_dword v84, v[8:9], off nt
	s_mov_b64 s[98:99], 0xab000
	v_lshl_add_u64 v[8:9], v[4:5], 0, s[98:99]
	global_load_dword v85, v[8:9], off nt
	s_mov_b64 s[98:99], 0xb4000
	v_lshl_add_u64 v[8:9], v[4:5], 0, s[98:99]
	global_load_dword v86, v[8:9], off nt
	s_mov_b64 s[98:99], 0xbd000
	v_lshl_add_u64 v[8:9], v[4:5], 0, s[98:99]
	global_load_dword v87, v[8:9], off nt
	s_mov_b64 s[98:99], 0xc6000
	v_lshl_add_u64 v[8:9], v[4:5], 0, s[98:99]
	global_load_dword v88, v[8:9], off nt
	s_mov_b64 s[98:99], 0xcf000
	v_lshl_add_u64 v[8:9], v[4:5], 0, s[98:99]
	global_load_dword v89, v[8:9], off nt
	s_mov_b64 s[98:99], 0xd8000
	v_lshl_add_u64 v[8:9], v[4:5], 0, s[98:99]
	global_load_dword v90, v[8:9], off nt
	s_mov_b64 s[98:99], 0xe1000
	v_lshl_add_u64 v[8:9], v[4:5], 0, s[98:99]
	global_load_dword v91, v[8:9], off nt
	s_mov_b64 s[98:99], 0xea000
	v_lshl_add_u64 v[8:9], v[4:5], 0, s[98:99]
	global_load_dword v92, v[8:9], off nt
	s_mov_b64 s[98:99], 0xf3000
	v_lshl_add_u64 v[8:9], v[4:5], 0, s[98:99]
	global_load_dword v93, v[8:9], off nt
	s_mov_b64 s[98:99], 0xfc000
	v_lshl_add_u64 v[8:9], v[4:5], 0, s[98:99]
	global_load_dword v94, v[8:9], off nt
	s_mov_b64 s[98:99], 0x105000
	v_lshl_add_u64 v[8:9], v[4:5], 0, s[98:99]
	global_load_dword v95, v[8:9], off nt
	s_mov_b64 s[98:99], 0x10e000
	v_lshl_add_u64 v[8:9], v[4:5], 0, s[98:99]
	global_load_dword v96, v[8:9], off nt
	s_mov_b64 s[98:99], 0x117000
	v_lshl_add_u64 v[8:9], v[4:5], 0, s[98:99]
	global_load_dword v97, v[8:9], off nt
	s_mov_b64 s[98:99], 0x120000
	v_lshl_add_u64 v[8:9], v[4:5], 0, s[98:99]
	global_load_dword v98, v[8:9], off nt
	s_mov_b64 s[98:99], 0x129000
	v_lshl_add_u64 v[8:9], v[4:5], 0, s[98:99]
	global_load_dword v99, v[8:9], off nt
	s_mov_b64 s[98:99], 0x132000
	v_lshl_add_u64 v[8:9], v[4:5], 0, s[98:99]
	global_load_dword v100, v[8:9], off nt
	s_mov_b64 s[98:99], 0x13b000
	v_lshl_add_u64 v[8:9], v[4:5], 0, s[98:99]
	global_load_dword v101, v[8:9], off nt
	s_mov_b64 s[98:99], 0x144000
	v_lshl_add_u64 v[8:9], v[4:5], 0, s[98:99]
	global_load_dword v102, v[8:9], off nt
	s_mov_b64 s[98:99], 0x14d000
	v_lshl_add_u64 v[8:9], v[4:5], 0, s[98:99]
	global_load_dword v103, v[8:9], off nt
	s_mov_b64 s[98:99], 0x156000
	v_lshl_add_u64 v[8:9], v[4:5], 0, s[98:99]
	global_load_dword v104, v[8:9], off nt
	s_mov_b64 s[98:99], 0x15f000
	v_lshl_add_u64 v[8:9], v[4:5], 0, s[98:99]
	global_load_dword v105, v[8:9], off nt
	s_mov_b64 s[98:99], 0x168000
	v_lshl_add_u64 v[8:9], v[4:5], 0, s[98:99]
	global_load_dword v106, v[8:9], off nt
	s_mov_b64 s[98:99], 0x171000
	v_lshl_add_u64 v[8:9], v[4:5], 0, s[98:99]
	global_load_dword v107, v[8:9], off nt
	s_mov_b64 s[98:99], 0x17a000
	v_lshl_add_u64 v[8:9], v[4:5], 0, s[98:99]
	global_load_dword v108, v[8:9], off nt
	s_mov_b64 s[98:99], 0x183000
	v_lshl_add_u64 v[8:9], v[4:5], 0, s[98:99]
	global_load_dword v109, v[8:9], off nt
	s_mov_b64 s[98:99], 0x18c000
	v_lshl_add_u64 v[8:9], v[4:5], 0, s[98:99]
	global_load_dword v110, v[8:9], off nt
	s_mov_b64 s[98:99], 0x195000
	v_lshl_add_u64 v[8:9], v[4:5], 0, s[98:99]
	global_load_dword v111, v[8:9], off nt
	s_mov_b64 s[98:99], 0x19e000
	v_lshl_add_u64 v[8:9], v[4:5], 0, s[98:99]
	global_load_dword v112, v[8:9], off nt
	s_mov_b64 s[98:99], 0x1a7000
	v_lshl_add_u64 v[8:9], v[4:5], 0, s[98:99]
	global_load_dword v113, v[8:9], off nt
	s_mov_b64 s[98:99], 0x1b0000
	v_lshl_add_u64 v[8:9], v[4:5], 0, s[98:99]
	global_load_dword v114, v[8:9], off nt
	s_mov_b64 s[98:99], 0x1b9000
	v_lshl_add_u64 v[8:9], v[4:5], 0, s[98:99]
	global_load_dword v115, v[8:9], off nt
	s_mov_b64 s[98:99], 0x1c2000
	v_lshl_add_u64 v[8:9], v[4:5], 0, s[98:99]
	global_load_dword v116, v[8:9], off nt
	s_mov_b64 s[98:99], 0x1cb000
	v_lshl_add_u64 v[8:9], v[4:5], 0, s[98:99]
	global_load_dword v117, v[8:9], off nt
	s_mov_b64 s[98:99], 0x1d4000
	v_lshl_add_u64 v[8:9], v[4:5], 0, s[98:99]
	global_load_dword v118, v[8:9], off nt
	s_mov_b64 s[98:99], 0x1dd000
	v_lshl_add_u64 v[8:9], v[4:5], 0, s[98:99]
	global_load_dword v119, v[8:9], off nt
	s_mov_b64 s[98:99], 0x1e6000
	v_lshl_add_u64 v[8:9], v[4:5], 0, s[98:99]
	global_load_dword v120, v[8:9], off nt
	s_mov_b64 s[98:99], 0x1ef000
	v_lshl_add_u64 v[8:9], v[4:5], 0, s[98:99]
	global_load_dword v121, v[8:9], off nt
	s_mov_b64 s[98:99], 0x1f8000
	v_lshl_add_u64 v[8:9], v[4:5], 0, s[98:99]
	global_load_dword v122, v[8:9], off nt
	s_mov_b64 s[98:99], 0x201000
	v_lshl_add_u64 v[8:9], v[4:5], 0, s[98:99]
	global_load_dword v123, v[8:9], off nt
	s_mov_b64 s[98:99], 0x20a000
	v_lshl_add_u64 v[8:9], v[4:5], 0, s[98:99]
	global_load_dword v124, v[8:9], off nt
	s_mov_b64 s[98:99], 0x213000
	v_lshl_add_u64 v[8:9], v[4:5], 0, s[98:99]
	global_load_dword v125, v[8:9], off nt
	s_mov_b64 s[98:99], 0x21c000
	v_lshl_add_u64 v[8:9], v[4:5], 0, s[98:99]
	global_load_dword v126, v[8:9], off nt
	s_mov_b64 s[98:99], 0x225000
	v_lshl_add_u64 v[8:9], v[4:5], 0, s[98:99]
	global_load_dword v127, v[8:9], off nt
	s_mov_b64 s[98:99], 0x22e000
	v_lshl_add_u64 v[8:9], v[4:5], 0, s[98:99]
	global_load_dword v128, v[8:9], off nt
	s_mov_b64 s[98:99], 0x237000
	v_lshl_add_u64 v[8:9], v[4:5], 0, s[98:99]
	global_load_dword v129, v[8:9], off nt
	s_mov_b64 s[98:99], 0x240000
	v_lshl_add_u64 v[8:9], v[4:5], 0, s[98:99]
	global_load_dword v130, v[8:9], off nt
	s_mov_b64 s[98:99], 0x249000
	v_lshl_add_u64 v[8:9], v[4:5], 0, s[98:99]
	global_load_dword v131, v[8:9], off nt
	s_mov_b64 s[98:99], 0x252000
	v_lshl_add_u64 v[8:9], v[4:5], 0, s[98:99]
	global_load_dword v132, v[8:9], off nt
	s_mov_b64 s[98:99], 0x25b000
	v_lshl_add_u64 v[8:9], v[4:5], 0, s[98:99]
	global_load_dword v133, v[8:9], off nt
	s_mov_b64 s[98:99], 0x264000
	v_lshl_add_u64 v[8:9], v[4:5], 0, s[98:99]
	global_load_dword v134, v[8:9], off nt
	s_mov_b64 s[98:99], 0x26d000
	v_lshl_add_u64 v[8:9], v[4:5], 0, s[98:99]
	global_load_dword v135, v[8:9], off nt
	s_mov_b64 s[98:99], 0x276000
	v_lshl_add_u64 v[8:9], v[4:5], 0, s[98:99]
	global_load_dword v136, v[8:9], off nt
	s_mov_b64 s[98:99], 0x27f000
	v_lshl_add_u64 v[8:9], v[4:5], 0, s[98:99]
	global_load_dword v137, v[8:9], off nt
	s_mov_b64 s[98:99], 0x288000
	v_lshl_add_u64 v[8:9], v[4:5], 0, s[98:99]
	global_load_dword v138, v[8:9], off nt
	s_mov_b64 s[98:99], 0x291000
	v_lshl_add_u64 v[8:9], v[4:5], 0, s[98:99]
	global_load_dword v139, v[8:9], off nt
	s_mov_b64 s[98:99], 0x29a000
	v_lshl_add_u64 v[8:9], v[4:5], 0, s[98:99]
	global_load_dword v140, v[8:9], off nt
	s_mov_b64 s[98:99], 0x2a3000
	v_lshl_add_u64 v[8:9], v[4:5], 0, s[98:99]
	global_load_dword v141, v[8:9], off nt
	s_mov_b64 s[98:99], 0x2ac000
	v_lshl_add_u64 v[8:9], v[4:5], 0, s[98:99]
	global_load_dword v142, v[8:9], off nt
	s_mov_b64 s[98:99], 0x2b5000
	v_lshl_add_u64 v[8:9], v[4:5], 0, s[98:99]
	global_load_dword v143, v[8:9], off nt
	s_mov_b64 s[98:99], 0x2be000
	v_lshl_add_u64 v[8:9], v[4:5], 0, s[98:99]
	global_load_dword v144, v[8:9], off nt
	s_mov_b64 s[98:99], 0x2c7000
	v_lshl_add_u64 v[8:9], v[4:5], 0, s[98:99]
	global_load_dword v145, v[8:9], off nt
	s_mov_b64 s[98:99], 0x2d0000
	v_lshl_add_u64 v[8:9], v[4:5], 0, s[98:99]
	global_load_dword v146, v[8:9], off nt
	s_mov_b64 s[98:99], 0x2d9000
	v_lshl_add_u64 v[8:9], v[4:5], 0, s[98:99]
	global_load_dword v147, v[8:9], off nt
	s_mov_b64 s[98:99], 0x2e2000
	v_lshl_add_u64 v[8:9], v[4:5], 0, s[98:99]
	global_load_dword v148, v[8:9], off nt
	s_mov_b64 s[98:99], 0x2eb000
	v_lshl_add_u64 v[8:9], v[4:5], 0, s[98:99]
	global_load_dword v149, v[8:9], off nt
	s_mov_b64 s[98:99], 0x2f4000
	v_lshl_add_u64 v[8:9], v[4:5], 0, s[98:99]
	global_load_dword v150, v[8:9], off nt
	s_mov_b64 s[98:99], 0x2fd000
	v_lshl_add_u64 v[8:9], v[4:5], 0, s[98:99]
	global_load_dword v151, v[8:9], off nt
	s_mov_b64 s[98:99], 0x306000
	v_lshl_add_u64 v[8:9], v[4:5], 0, s[98:99]
	global_load_dword v152, v[8:9], off nt
	s_mov_b64 s[98:99], 0x30f000
	v_lshl_add_u64 v[8:9], v[4:5], 0, s[98:99]
	global_load_dword v153, v[8:9], off nt
	s_mov_b64 s[98:99], 0x318000
	v_lshl_add_u64 v[8:9], v[4:5], 0, s[98:99]
	global_load_dword v154, v[8:9], off nt
	s_mov_b64 s[98:99], 0x321000
	v_lshl_add_u64 v[8:9], v[4:5], 0, s[98:99]
	global_load_dword v155, v[8:9], off nt
	s_mov_b64 s[98:99], 0x32a000
	v_lshl_add_u64 v[8:9], v[4:5], 0, s[98:99]
	global_load_dword v156, v[8:9], off nt
	s_mov_b64 s[98:99], 0x333000
	v_lshl_add_u64 v[8:9], v[4:5], 0, s[98:99]
	global_load_dword v157, v[8:9], off nt
	s_mov_b64 s[98:99], 0x33c000
	v_lshl_add_u64 v[8:9], v[4:5], 0, s[98:99]
	global_load_dword v158, v[8:9], off nt
	s_mov_b64 s[98:99], 0x345000
	v_lshl_add_u64 v[8:9], v[4:5], 0, s[98:99]
	global_load_dword v159, v[8:9], off nt
	s_mov_b64 s[98:99], 0x34e000
	v_lshl_add_u64 v[8:9], v[4:5], 0, s[98:99]
	global_load_dword v160, v[8:9], off nt
	s_mov_b64 s[98:99], 0x357000
	v_lshl_add_u64 v[8:9], v[4:5], 0, s[98:99]
	global_load_dword v161, v[8:9], off nt
	s_mov_b64 s[98:99], 0x360000
	v_lshl_add_u64 v[8:9], v[4:5], 0, s[98:99]
	global_load_dword v162, v[8:9], off nt
	s_mov_b64 s[98:99], 0x369000
	v_lshl_add_u64 v[8:9], v[4:5], 0, s[98:99]
	global_load_dword v163, v[8:9], off nt
	s_mov_b64 s[98:99], 0x372000
	v_lshl_add_u64 v[8:9], v[4:5], 0, s[98:99]
	global_load_dword v164, v[8:9], off nt
	s_mov_b64 s[98:99], 0x37b000
	v_lshl_add_u64 v[8:9], v[4:5], 0, s[98:99]
	global_load_dword v165, v[8:9], off nt
	s_mov_b64 s[98:99], 0x384000
	v_lshl_add_u64 v[8:9], v[4:5], 0, s[98:99]
	global_load_dword v166, v[8:9], off nt
	s_mov_b64 s[98:99], 0x38d000
	v_lshl_add_u64 v[8:9], v[4:5], 0, s[98:99]
	global_load_dword v167, v[8:9], off nt
	s_mov_b64 s[98:99], 0x396000
	v_lshl_add_u64 v[8:9], v[4:5], 0, s[98:99]
	global_load_dword v168, v[8:9], off nt
	s_mov_b64 s[98:99], 0x39f000
	v_lshl_add_u64 v[8:9], v[4:5], 0, s[98:99]
	global_load_dword v169, v[8:9], off nt
	s_mov_b64 s[98:99], 0x3a8000
	v_lshl_add_u64 v[8:9], v[4:5], 0, s[98:99]
	global_load_dword v170, v[8:9], off nt
	s_mov_b64 s[98:99], 0x3b1000
	v_lshl_add_u64 v[8:9], v[4:5], 0, s[98:99]
	global_load_dword v171, v[8:9], off nt
	s_mov_b64 s[98:99], 0x3ba000
	v_lshl_add_u64 v[8:9], v[4:5], 0, s[98:99]
	global_load_dword v172, v[8:9], off nt
	s_mov_b64 s[98:99], 0x3c3000
	v_lshl_add_u64 v[8:9], v[4:5], 0, s[98:99]
	global_load_dword v173, v[8:9], off nt
	s_mov_b64 s[98:99], 0x3cc000
	v_lshl_add_u64 v[8:9], v[4:5], 0, s[98:99]
	global_load_dword v174, v[8:9], off nt
	s_mov_b64 s[98:99], 0x3d5000
	v_lshl_add_u64 v[8:9], v[4:5], 0, s[98:99]
	global_load_dword v175, v[8:9], off nt
	s_mov_b64 s[98:99], 0x3de000
	v_lshl_add_u64 v[8:9], v[4:5], 0, s[98:99]
	global_load_dword v176, v[8:9], off nt
	s_mov_b64 s[98:99], 0x3e7000
	v_lshl_add_u64 v[8:9], v[4:5], 0, s[98:99]
	global_load_dword v177, v[8:9], off nt
	s_mov_b64 s[98:99], 0x3f0000
	v_lshl_add_u64 v[8:9], v[4:5], 0, s[98:99]
	global_load_dword v178, v[8:9], off nt
	s_mov_b64 s[98:99], 0x3f9000
	v_lshl_add_u64 v[8:9], v[4:5], 0, s[98:99]
	global_load_dword v179, v[8:9], off nt
	s_mov_b64 s[98:99], 0x402000
	v_lshl_add_u64 v[8:9], v[4:5], 0, s[98:99]
	global_load_dword v180, v[8:9], off nt
	s_mov_b64 s[98:99], 0x40b000
	v_lshl_add_u64 v[8:9], v[4:5], 0, s[98:99]
	global_load_dword v181, v[8:9], off nt
	s_mov_b64 s[98:99], 0x414000
	v_lshl_add_u64 v[8:9], v[4:5], 0, s[98:99]
	global_load_dword v182, v[8:9], off nt
	s_mov_b64 s[98:99], 0x41d000
	v_lshl_add_u64 v[8:9], v[4:5], 0, s[98:99]
	global_load_dword v183, v[8:9], off nt
	s_mov_b64 s[98:99], 0x426000
	v_lshl_add_u64 v[8:9], v[4:5], 0, s[98:99]
	global_load_dword v184, v[8:9], off nt
	s_mov_b64 s[98:99], 0x42f000
	v_lshl_add_u64 v[8:9], v[4:5], 0, s[98:99]
	global_load_dword v185, v[8:9], off nt
	s_mov_b64 s[98:99], 0x438000
	v_lshl_add_u64 v[8:9], v[4:5], 0, s[98:99]
	global_load_dword v186, v[8:9], off nt
	s_mov_b64 s[98:99], 0x441000
	v_lshl_add_u64 v[8:9], v[4:5], 0, s[98:99]
	global_load_dword v187, v[8:9], off nt
	s_mov_b64 s[98:99], 0x44a000
	v_lshl_add_u64 v[8:9], v[4:5], 0, s[98:99]
	global_load_dword v188, v[8:9], off nt
	s_mov_b64 s[98:99], 0x453000
	v_lshl_add_u64 v[8:9], v[4:5], 0, s[98:99]
	global_load_dword v189, v[8:9], off nt
	s_mov_b64 s[98:99], 0x45c000
	v_lshl_add_u64 v[8:9], v[4:5], 0, s[98:99]
	global_load_dword v190, v[8:9], off nt
	s_mov_b64 s[98:99], 0x465000
	v_lshl_add_u64 v[8:9], v[4:5], 0, s[98:99]
	global_load_dword v191, v[8:9], off nt
	s_mov_b64 s[98:99], 0x46e000
	v_lshl_add_u64 v[8:9], v[4:5], 0, s[98:99]
	global_load_dword v192, v[8:9], off nt
	s_mov_b64 s[98:99], 0x477000
	v_lshl_add_u64 v[8:9], v[4:5], 0, s[98:99]
	global_load_dword v193, v[8:9], off nt
	v_mov_b32_e32 v9, s4
	ds_read_b128 v[10:13], v9
	ds_read_b128 v[14:17], v9 offset:16
	ds_read_b128 v[18:21], v9 offset:32
	ds_read_b128 v[22:25], v9 offset:48
	ds_read_b128 v[26:29], v9 offset:4096
	s_waitcnt lgkmcnt(4)
	s_waitcnt vmcnt(63)
	v_fma_f32 v0, v66, v10, 0
	v_fmac_f32_e32 v0, v67, v11
	v_fmac_f32_e32 v0, v68, v12
	v_fmac_f32_e32 v0, v69, v13
	ds_read_b128 v[10:13], v9 offset:4112
	s_waitcnt lgkmcnt(1)
	v_fma_f32 v7, v66, v26, 0
	v_fmac_f32_e32 v7, v67, v27
	v_fmac_f32_e32 v7, v68, v28
	v_fmac_f32_e32 v7, v69, v29
	s_waitcnt lgkmcnt(0)
	v_fmac_f32_e32 v7, v70, v10
	v_fmac_f32_e32 v7, v71, v11
	ds_read_b128 v[30:33], v9 offset:8192
	v_fmac_f32_e32 v7, v72, v12
	v_fmac_f32_e32 v7, v73, v13
	ds_read_b128 v[10:13], v9 offset:4128
	ds_read_b128 v[26:29], v9 offset:8208
	s_waitcnt lgkmcnt(2)
	v_fma_f32 v8, v66, v30, 0
	v_fmac_f32_e32 v0, v70, v14
	v_fmac_f32_e32 v8, v67, v31
	v_fmac_f32_e32 v0, v71, v15
	s_waitcnt lgkmcnt(1)
	v_fmac_f32_e32 v7, v74, v10
	v_fmac_f32_e32 v8, v68, v32
	v_fmac_f32_e32 v0, v72, v16
	v_fmac_f32_e32 v7, v75, v11
	v_fmac_f32_e32 v8, v69, v33
	v_fmac_f32_e32 v0, v73, v17
	ds_read_b128 v[14:17], v9 offset:8224
	v_fmac_f32_e32 v7, v76, v12
	v_fmac_f32_e32 v7, v77, v13
	ds_read_b128 v[10:13], v9 offset:4144
	s_waitcnt lgkmcnt(2)
	v_fmac_f32_e32 v8, v70, v26
	v_fmac_f32_e32 v8, v71, v27
	v_fmac_f32_e32 v0, v74, v18
	v_fmac_f32_e32 v8, v72, v28
	v_fmac_f32_e32 v0, v75, v19
	v_fmac_f32_e32 v8, v73, v29
	v_fmac_f32_e32 v0, v76, v20
	v_fmac_f32_e32 v0, v77, v21
	ds_read_b128 v[18:21], v9 offset:8256
	s_waitcnt lgkmcnt(2)
	v_fmac_f32_e32 v8, v74, v14
	v_fmac_f32_e32 v8, v75, v15
	v_fmac_f32_e32 v8, v76, v16
	v_fmac_f32_e32 v8, v77, v17
	s_waitcnt lgkmcnt(1)
	v_fmac_f32_e32 v7, v78, v10
	ds_read_b128 v[14:17], v9 offset:8240
	v_fmac_f32_e32 v7, v79, v11
	v_fmac_f32_e32 v7, v80, v12
	v_fmac_f32_e32 v7, v81, v13
	ds_read_b128 v[10:13], v9 offset:64
	v_fmac_f32_e32 v0, v78, v22
	s_waitcnt lgkmcnt(1)
	v_fmac_f32_e32 v8, v78, v14
	v_fmac_f32_e32 v0, v79, v23
	v_fmac_f32_e32 v8, v79, v15
	v_fmac_f32_e32 v0, v80, v24
	v_fmac_f32_e32 v8, v80, v16
	v_fmac_f32_e32 v0, v81, v25
	v_fmac_f32_e32 v8, v81, v17
	ds_read_b128 v[14:17], v9 offset:4160
	s_waitcnt lgkmcnt(1)
	v_fmac_f32_e32 v0, v82, v10
	v_fmac_f32_e32 v0, v83, v11
	v_fmac_f32_e32 v0, v84, v12
	v_fmac_f32_e32 v0, v85, v13
	ds_read_b128 v[10:13], v9 offset:80
	s_waitcnt lgkmcnt(1)
	v_fmac_f32_e32 v7, v82, v14
	v_fmac_f32_e32 v7, v83, v15
	v_fmac_f32_e32 v7, v84, v16
	v_fmac_f32_e32 v7, v85, v17
	ds_read_b128 v[14:17], v9 offset:4176
	s_waitcnt lgkmcnt(1)
	v_fmac_f32_e32 v0, v86, v10
	v_fmac_f32_e32 v0, v87, v11
	v_fmac_f32_e32 v0, v88, v12
	v_fmac_f32_e32 v0, v89, v13
	ds_read_b128 v[10:13], v9 offset:96
	s_waitcnt lgkmcnt(1)
	v_fmac_f32_e32 v7, v86, v14
	v_fmac_f32_e32 v7, v87, v15
	v_fmac_f32_e32 v7, v88, v16
	v_fmac_f32_e32 v7, v89, v17
	ds_read_b128 v[14:17], v9 offset:4192
	s_waitcnt lgkmcnt(1)
	v_fmac_f32_e32 v0, v90, v10
	v_fmac_f32_e32 v0, v91, v11
	v_fmac_f32_e32 v0, v92, v12
	v_fmac_f32_e32 v0, v93, v13
	ds_read_b128 v[10:13], v9 offset:112
	s_waitcnt lgkmcnt(1)
	v_fmac_f32_e32 v7, v90, v14
	v_fmac_f32_e32 v7, v91, v15
	v_fmac_f32_e32 v7, v92, v16
	v_fmac_f32_e32 v7, v93, v17
	ds_read_b128 v[14:17], v9 offset:4208
	s_waitcnt lgkmcnt(1)
	v_fmac_f32_e32 v0, v94, v10
	v_fmac_f32_e32 v0, v95, v11
	v_fmac_f32_e32 v8, v82, v18
	v_fmac_f32_e32 v8, v83, v19
	s_nop 0
	v_fmac_f32_e32 v8, v84, v20
	v_fmac_f32_e32 v0, v96, v12
	v_fmac_f32_e32 v8, v85, v21
	v_fmac_f32_e32 v0, v97, v13
	ds_read_b128 v[10:13], v9 offset:128
	s_waitcnt lgkmcnt(1)
	v_fmac_f32_e32 v7, v94, v14
	v_fmac_f32_e32 v7, v95, v15
	v_fmac_f32_e32 v7, v96, v16
	v_fmac_f32_e32 v7, v97, v17
	ds_read_b128 v[14:17], v9 offset:4224
	s_waitcnt lgkmcnt(1)
	v_fmac_f32_e32 v0, v98, v10
	v_fmac_f32_e32 v0, v99, v11
	v_fmac_f32_e32 v0, v100, v12
	v_fmac_f32_e32 v0, v101, v13
	ds_read_b128 v[10:13], v9 offset:144
	s_waitcnt lgkmcnt(1)
	v_fmac_f32_e32 v7, v98, v14
	v_fmac_f32_e32 v7, v99, v15
	v_fmac_f32_e32 v7, v100, v16
	v_fmac_f32_e32 v7, v101, v17
	ds_read_b128 v[14:17], v9 offset:4240
	s_waitcnt lgkmcnt(1)
	v_fmac_f32_e32 v0, v102, v10
	v_fmac_f32_e32 v0, v103, v11
	v_fmac_f32_e32 v0, v104, v12
	v_fmac_f32_e32 v0, v105, v13
	ds_read_b128 v[10:13], v9 offset:160
	s_waitcnt lgkmcnt(1)
	v_fmac_f32_e32 v7, v102, v14
	v_fmac_f32_e32 v7, v103, v15
	v_fmac_f32_e32 v7, v104, v16
	v_fmac_f32_e32 v7, v105, v17
	ds_read_b128 v[14:17], v9 offset:4256
	s_waitcnt lgkmcnt(1)
	v_fmac_f32_e32 v0, v106, v10
	v_fmac_f32_e32 v0, v107, v11
	v_fmac_f32_e32 v0, v108, v12
	v_fmac_f32_e32 v0, v109, v13
	ds_read_b128 v[10:13], v9 offset:176
	s_waitcnt lgkmcnt(1)
	v_fmac_f32_e32 v7, v106, v14
	v_fmac_f32_e32 v7, v107, v15
	v_fmac_f32_e32 v7, v108, v16
	v_fmac_f32_e32 v7, v109, v17
	ds_read_b128 v[14:17], v9 offset:4272
	s_waitcnt lgkmcnt(1)
	v_fmac_f32_e32 v0, v110, v10
	v_fmac_f32_e32 v0, v111, v11
	v_fmac_f32_e32 v0, v112, v12
	v_fmac_f32_e32 v0, v113, v13
	ds_read_b128 v[10:13], v9 offset:192
	ds_read_b128 v[18:21], v9 offset:8272
	s_waitcnt lgkmcnt(2)
	v_fmac_f32_e32 v7, v110, v14
	v_fmac_f32_e32 v7, v111, v15
	v_fmac_f32_e32 v7, v112, v16
	v_fmac_f32_e32 v7, v113, v17
	ds_read_b128 v[14:17], v9 offset:4288
	s_waitcnt lgkmcnt(2)
	v_fmac_f32_e32 v0, v114, v10
	v_fmac_f32_e32 v0, v115, v11
	s_waitcnt lgkmcnt(1)
	v_fmac_f32_e32 v8, v86, v18
	v_fmac_f32_e32 v0, v116, v12
	v_fmac_f32_e32 v8, v87, v19
	v_fmac_f32_e32 v0, v117, v13
	ds_read_b128 v[10:13], v9 offset:208
	v_fmac_f32_e32 v8, v88, v20
	v_fmac_f32_e32 v8, v89, v21
	ds_read_b128 v[18:21], v9 offset:8288
	s_waitcnt lgkmcnt(2)
	v_fmac_f32_e32 v7, v114, v14
	v_fmac_f32_e32 v7, v115, v15
	v_fmac_f32_e32 v7, v116, v16
	v_fmac_f32_e32 v7, v117, v17
	ds_read_b128 v[14:17], v9 offset:4304
	s_waitcnt lgkmcnt(2)
	v_fmac_f32_e32 v0, v118, v10
	v_fmac_f32_e32 v0, v119, v11
	s_waitcnt lgkmcnt(1)
	v_fmac_f32_e32 v8, v90, v18
	v_fmac_f32_e32 v0, v120, v12
	v_fmac_f32_e32 v8, v91, v19
	v_fmac_f32_e32 v0, v121, v13
	ds_read_b128 v[10:13], v9 offset:224
	v_fmac_f32_e32 v8, v92, v20
	v_fmac_f32_e32 v8, v93, v21
	ds_read_b128 v[18:21], v9 offset:8304
	s_waitcnt lgkmcnt(2)
	v_fmac_f32_e32 v7, v118, v14
	v_fmac_f32_e32 v7, v119, v15
	v_fmac_f32_e32 v7, v120, v16
	v_fmac_f32_e32 v7, v121, v17
	ds_read_b128 v[14:17], v9 offset:4320
	s_waitcnt lgkmcnt(2)
	v_fmac_f32_e32 v0, v122, v10
	v_fmac_f32_e32 v0, v123, v11
	s_waitcnt lgkmcnt(1)
	v_fmac_f32_e32 v8, v94, v18
	v_fmac_f32_e32 v0, v124, v12
	v_fmac_f32_e32 v8, v95, v19
	v_fmac_f32_e32 v0, v125, v13
	ds_read_b128 v[10:13], v9 offset:240
	v_fmac_f32_e32 v8, v96, v20
	v_fmac_f32_e32 v8, v97, v21
	ds_read_b128 v[18:21], v9 offset:8320
	s_waitcnt lgkmcnt(2)
	v_fmac_f32_e32 v7, v122, v14
	v_fmac_f32_e32 v7, v123, v15
	v_fmac_f32_e32 v7, v124, v16
	v_fmac_f32_e32 v7, v125, v17
	ds_read_b128 v[14:17], v9 offset:4336
	s_waitcnt lgkmcnt(2)
	v_fmac_f32_e32 v0, v126, v10
	v_fmac_f32_e32 v0, v127, v11
	s_waitcnt lgkmcnt(1)
	v_fmac_f32_e32 v8, v98, v18
	v_fmac_f32_e32 v8, v99, v19
	s_nop 0
	v_fmac_f32_e32 v8, v100, v20
	v_fmac_f32_e32 v8, v101, v21
	ds_read_b128 v[18:21], v9 offset:8336
	s_waitcnt lgkmcnt(0)
	v_fmac_f32_e32 v8, v102, v18
	v_fmac_f32_e32 v8, v103, v19
	s_nop 0
	v_fmac_f32_e32 v8, v104, v20
	v_fmac_f32_e32 v8, v105, v21
	ds_read_b128 v[18:21], v9 offset:8352
	s_waitcnt lgkmcnt(0)
	v_fmac_f32_e32 v8, v106, v18
	v_fmac_f32_e32 v8, v107, v19
	s_nop 0
	v_fmac_f32_e32 v8, v108, v20
	v_fmac_f32_e32 v8, v109, v21
	ds_read_b128 v[18:21], v9 offset:8368
	s_waitcnt lgkmcnt(0)
	v_fmac_f32_e32 v8, v110, v18
	v_fmac_f32_e32 v8, v111, v19
	s_nop 0
	v_fmac_f32_e32 v8, v112, v20
	v_fmac_f32_e32 v8, v113, v21
	ds_read_b128 v[18:21], v9 offset:8384
	s_waitcnt lgkmcnt(0)
	v_fmac_f32_e32 v8, v114, v18
	v_fmac_f32_e32 v8, v115, v19
	s_nop 0
	v_fmac_f32_e32 v8, v116, v20
	v_fmac_f32_e32 v8, v117, v21
	ds_read_b128 v[18:21], v9 offset:8400
	s_waitcnt lgkmcnt(0)
	v_fmac_f32_e32 v8, v118, v18
	v_fmac_f32_e32 v8, v119, v19
	s_nop 0
	v_fmac_f32_e32 v8, v120, v20
	v_fmac_f32_e32 v8, v121, v21
	ds_read_b128 v[18:21], v9 offset:8416
	s_waitcnt lgkmcnt(0)
	v_fmac_f32_e32 v8, v122, v18
	v_fmac_f32_e32 v8, v123, v19
	v_fmac_f32_e32 v8, v124, v20
	v_fmac_f32_e32 v8, v125, v21
	ds_read_b128 v[18:21], v9 offset:8432
	v_fmac_f32_e32 v7, v126, v14
	s_waitcnt lgkmcnt(0)
	v_fmac_f32_e32 v8, v126, v18
	v_fmac_f32_e32 v7, v127, v15
	s_nop 0
	v_fmac_f32_e32 v8, v127, v19
	v_fmac_f32_e32 v0, v128, v12
	v_fmac_f32_e32 v7, v128, v16
	v_fmac_f32_e32 v8, v128, v20
	v_fmac_f32_e32 v0, v129, v13
	v_fmac_f32_e32 v7, v129, v17
	v_fmac_f32_e32 v8, v129, v21
	ds_read_b128 v[10:13], v9 offset:256
	ds_read_b128 v[14:17], v9 offset:4352
	ds_read_b128 v[18:21], v9 offset:8448
	s_waitcnt lgkmcnt(2)
	v_fmac_f32_e32 v0, v130, v10
	s_waitcnt vmcnt(62)
	v_fmac_f32_e32 v0, v131, v11
	s_waitcnt vmcnt(61)
	v_fmac_f32_e32 v0, v132, v12
	s_waitcnt vmcnt(60)
	v_fmac_f32_e32 v0, v133, v13
	ds_read_b128 v[10:13], v9 offset:272
	s_waitcnt lgkmcnt(2)
	v_fmac_f32_e32 v7, v130, v14
	v_fmac_f32_e32 v7, v131, v15
	v_fmac_f32_e32 v7, v132, v16
	v_fmac_f32_e32 v7, v133, v17
	ds_read_b128 v[14:17], v9 offset:4368
	s_waitcnt lgkmcnt(1)
	s_waitcnt vmcnt(59)
	v_fmac_f32_e32 v0, v134, v10
	s_waitcnt vmcnt(58)
	v_fmac_f32_e32 v0, v135, v11
	s_waitcnt vmcnt(57)
	v_fmac_f32_e32 v0, v136, v12
	s_waitcnt vmcnt(56)
	v_fmac_f32_e32 v0, v137, v13
	ds_read_b128 v[10:13], v9 offset:288
	s_waitcnt lgkmcnt(1)
	v_fmac_f32_e32 v7, v134, v14
	v_fmac_f32_e32 v7, v135, v15
	v_fmac_f32_e32 v7, v136, v16
	v_fmac_f32_e32 v7, v137, v17
	ds_read_b128 v[14:17], v9 offset:4384
	s_waitcnt lgkmcnt(1)
	s_waitcnt vmcnt(55)
	v_fmac_f32_e32 v0, v138, v10
	s_waitcnt vmcnt(54)
	v_fmac_f32_e32 v0, v139, v11
	s_waitcnt vmcnt(53)
	v_fmac_f32_e32 v0, v140, v12
	s_waitcnt vmcnt(52)
	v_fmac_f32_e32 v0, v141, v13
	ds_read_b128 v[10:13], v9 offset:304
	s_waitcnt lgkmcnt(1)
	v_fmac_f32_e32 v7, v138, v14
	v_fmac_f32_e32 v7, v139, v15
	v_fmac_f32_e32 v7, v140, v16
	v_fmac_f32_e32 v7, v141, v17
	ds_read_b128 v[14:17], v9 offset:4400
	s_waitcnt lgkmcnt(1)
	s_waitcnt vmcnt(51)
	v_fmac_f32_e32 v0, v142, v10
	s_waitcnt vmcnt(50)
	v_fmac_f32_e32 v0, v143, v11
	s_waitcnt vmcnt(49)
	v_fmac_f32_e32 v0, v144, v12
	s_waitcnt vmcnt(48)
	v_fmac_f32_e32 v0, v145, v13
	ds_read_b128 v[10:13], v9 offset:320
	v_fmac_f32_e32 v8, v130, v18
	v_fmac_f32_e32 v8, v131, v19
	s_waitcnt lgkmcnt(1)
	v_fmac_f32_e32 v7, v142, v14
	v_fmac_f32_e32 v8, v132, v20
	v_fmac_f32_e32 v7, v143, v15
	v_fmac_f32_e32 v8, v133, v21
	ds_read_b128 v[18:21], v9 offset:8464
	v_fmac_f32_e32 v7, v144, v16
	v_fmac_f32_e32 v7, v145, v17
	ds_read_b128 v[14:17], v9 offset:4416
	s_waitcnt lgkmcnt(2)
	s_waitcnt vmcnt(47)
	v_fmac_f32_e32 v0, v146, v10
	s_waitcnt vmcnt(46)
	v_fmac_f32_e32 v0, v147, v11
	s_waitcnt vmcnt(45)
	v_fmac_f32_e32 v0, v148, v12
	s_waitcnt vmcnt(44)
	v_fmac_f32_e32 v0, v149, v13
	ds_read_b128 v[10:13], v9 offset:336
	s_waitcnt lgkmcnt(2)
	v_fmac_f32_e32 v8, v134, v18
	v_fmac_f32_e32 v8, v135, v19
	s_waitcnt lgkmcnt(1)
	v_fmac_f32_e32 v7, v146, v14
	v_fmac_f32_e32 v8, v136, v20
	v_fmac_f32_e32 v7, v147, v15
	v_fmac_f32_e32 v8, v137, v21
	ds_read_b128 v[18:21], v9 offset:8480
	v_fmac_f32_e32 v7, v148, v16
	v_fmac_f32_e32 v7, v149, v17
	ds_read_b128 v[14:17], v9 offset:4432
	s_waitcnt lgkmcnt(2)
	s_waitcnt vmcnt(43)
	v_fmac_f32_e32 v0, v150, v10
	s_waitcnt vmcnt(42)
	v_fmac_f32_e32 v0, v151, v11
	s_waitcnt vmcnt(41)
	v_fmac_f32_e32 v0, v152, v12
	s_waitcnt vmcnt(40)
	v_fmac_f32_e32 v0, v153, v13
	ds_read_b128 v[10:13], v9 offset:352
	s_waitcnt lgkmcnt(2)
	v_fmac_f32_e32 v8, v138, v18
	v_fmac_f32_e32 v8, v139, v19
	s_waitcnt lgkmcnt(1)
	v_fmac_f32_e32 v7, v150, v14
	v_fmac_f32_e32 v8, v140, v20
	v_fmac_f32_e32 v7, v151, v15
	v_fmac_f32_e32 v8, v141, v21
	ds_read_b128 v[18:21], v9 offset:8496
	v_fmac_f32_e32 v7, v152, v16
	v_fmac_f32_e32 v7, v153, v17
	ds_read_b128 v[14:17], v9 offset:4448
	s_waitcnt lgkmcnt(2)
	s_waitcnt vmcnt(39)
	v_fmac_f32_e32 v0, v154, v10
	s_waitcnt vmcnt(38)
	v_fmac_f32_e32 v0, v155, v11
	s_waitcnt vmcnt(37)
	v_fmac_f32_e32 v0, v156, v12
	s_waitcnt vmcnt(36)
	v_fmac_f32_e32 v0, v157, v13
	ds_read_b128 v[10:13], v9 offset:368
	s_waitcnt lgkmcnt(2)
	v_fmac_f32_e32 v8, v142, v18
	v_fmac_f32_e32 v8, v143, v19
	s_waitcnt lgkmcnt(1)
	v_fmac_f32_e32 v7, v154, v14
	v_fmac_f32_e32 v8, v144, v20
	v_fmac_f32_e32 v7, v155, v15
	v_fmac_f32_e32 v8, v145, v21
	ds_read_b128 v[18:21], v9 offset:8512
	v_fmac_f32_e32 v7, v156, v16
	v_fmac_f32_e32 v7, v157, v17
	ds_read_b128 v[14:17], v9 offset:4464
	s_waitcnt lgkmcnt(2)
	s_waitcnt vmcnt(35)
	v_fmac_f32_e32 v0, v158, v10
	s_waitcnt vmcnt(34)
	v_fmac_f32_e32 v0, v159, v11
	s_waitcnt lgkmcnt(1)
	v_fmac_f32_e32 v8, v146, v18
	v_fmac_f32_e32 v8, v147, v19
	v_fmac_f32_e32 v8, v148, v20
	s_nop 0
	v_fmac_f32_e32 v8, v149, v21
	ds_read_b128 v[18:21], v9 offset:8528
	s_waitcnt vmcnt(33)
	v_fmac_f32_e32 v0, v160, v12
	s_waitcnt vmcnt(32)
	v_fmac_f32_e32 v0, v161, v13
	s_waitcnt lgkmcnt(0)
	v_fmac_f32_e32 v8, v150, v18
	v_fmac_f32_e32 v7, v158, v14
	v_fmac_f32_e32 v8, v151, v19
	s_nop 0
	v_fmac_f32_e32 v8, v152, v20
	v_fmac_f32_e32 v7, v159, v15
	v_fmac_f32_e32 v8, v153, v21
	ds_read_b128 v[18:21], v9 offset:8544
	s_waitcnt lgkmcnt(0)
	v_fmac_f32_e32 v8, v154, v18
	v_fmac_f32_e32 v8, v155, v19
	s_nop 0
	v_fmac_f32_e32 v8, v156, v20
	v_fmac_f32_e32 v8, v157, v21
	ds_read_b128 v[18:21], v9 offset:8560
	v_fmac_f32_e32 v7, v160, v16
	s_nop 0
	v_fmac_f32_e32 v7, v161, v17
	s_waitcnt lgkmcnt(0)
	v_fmac_f32_e32 v8, v158, v18
	v_fmac_f32_e32 v8, v159, v19
	s_nop 0
	v_fmac_f32_e32 v8, v160, v20
	v_fmac_f32_e32 v8, v161, v21
	ds_read_b128 v[46:49], v9 offset:4480
	ds_read_b128 v[42:45], v9 offset:384
	ds_read_b128 v[50:53], v9 offset:8576
	s_waitcnt lgkmcnt(2)
	s_waitcnt vmcnt(31)
	v_fmac_f32_e32 v7, v162, v46
	s_waitcnt vmcnt(30)
	v_fmac_f32_e32 v7, v163, v47
	s_waitcnt vmcnt(29)
	v_fmac_f32_e32 v7, v164, v48
	s_waitcnt lgkmcnt(1)
	v_fmac_f32_e32 v0, v162, v42
	s_waitcnt vmcnt(28)
	v_fmac_f32_e32 v7, v165, v49
	ds_read_b128 v[46:49], v9 offset:8592
	s_waitcnt lgkmcnt(1)
	v_fmac_f32_e32 v8, v162, v50
	v_fmac_f32_e32 v0, v163, v43
	v_fmac_f32_e32 v8, v163, v51
	v_fmac_f32_e32 v0, v164, v44
	v_fmac_f32_e32 v8, v164, v52
	v_fmac_f32_e32 v0, v165, v45
	v_fmac_f32_e32 v8, v165, v53
	ds_read_b128 v[38:41], v9 offset:400
	ds_read_b128 v[42:45], v9 offset:4496
	s_waitcnt lgkmcnt(2)
	s_waitcnt vmcnt(27)
	v_fmac_f32_e32 v8, v166, v46
	s_waitcnt vmcnt(26)
	v_fmac_f32_e32 v8, v167, v47
	s_waitcnt vmcnt(25)
	v_fmac_f32_e32 v8, v168, v48
	s_waitcnt lgkmcnt(1)
	v_fmac_f32_e32 v0, v166, v38
	s_waitcnt lgkmcnt(0)
	v_fmac_f32_e32 v7, v166, v42
	v_fmac_f32_e32 v0, v167, v39
	v_fmac_f32_e32 v7, v167, v43
	v_fmac_f32_e32 v0, v168, v40
	v_fmac_f32_e32 v7, v168, v44
	s_waitcnt vmcnt(24)
	v_fmac_f32_e32 v0, v169, v41
	v_fmac_f32_e32 v7, v169, v45
	ds_read_b128 v[38:41], v9 offset:416
	ds_read_b128 v[42:45], v9 offset:4512
	v_fmac_f32_e32 v8, v169, v49
	ds_read_b128 v[46:49], v9 offset:8608
	s_waitcnt lgkmcnt(2)
	s_waitcnt vmcnt(23)
	v_fmac_f32_e32 v0, v170, v38
	s_waitcnt lgkmcnt(1)
	v_fmac_f32_e32 v7, v170, v42
	s_waitcnt vmcnt(22)
	v_fmac_f32_e32 v7, v171, v43
	s_waitcnt vmcnt(21)
	v_fmac_f32_e32 v7, v172, v44
	v_fmac_f32_e32 v0, v171, v39
	s_waitcnt vmcnt(20)
	v_fmac_f32_e32 v7, v173, v45
	ds_read_b128 v[42:45], v9 offset:8624
	s_waitcnt lgkmcnt(1)
	v_fmac_f32_e32 v8, v170, v46
	v_fmac_f32_e32 v8, v171, v47
	v_fmac_f32_e32 v0, v172, v40
	ds_read_b128 v[24:27], v9 offset:432
	v_fmac_f32_e32 v0, v173, v41
	ds_read_b128 v[38:41], v9 offset:4528
	v_fmac_f32_e32 v8, v172, v48
	v_fmac_f32_e32 v8, v173, v49
	s_waitcnt lgkmcnt(1)
	s_waitcnt vmcnt(19)
	v_fmac_f32_e32 v0, v174, v24
	v_fmac_f32_e32 v8, v174, v42
	s_waitcnt lgkmcnt(0)
	v_fmac_f32_e32 v7, v174, v38
	s_waitcnt vmcnt(18)
	v_fmac_f32_e32 v0, v175, v25
	v_fmac_f32_e32 v7, v175, v39
	v_fmac_f32_e32 v8, v175, v43
	s_waitcnt vmcnt(17)
	v_fmac_f32_e32 v0, v176, v26
	v_fmac_f32_e32 v7, v176, v40
	v_fmac_f32_e32 v8, v176, v44
	s_waitcnt vmcnt(16)
	v_fmac_f32_e32 v0, v177, v27
	ds_read_b128 v[24:27], v9 offset:448
	v_fmac_f32_e32 v7, v177, v41
	v_fmac_f32_e32 v8, v177, v45
	ds_read_b128 v[38:41], v9 offset:4544
	ds_read_b128 v[42:45], v9 offset:8640
	s_waitcnt lgkmcnt(2)
	s_waitcnt vmcnt(15)
	v_fmac_f32_e32 v0, v178, v24
	s_waitcnt vmcnt(14)
	v_fmac_f32_e32 v0, v179, v25
	s_waitcnt vmcnt(13)
	v_fmac_f32_e32 v0, v180, v26
	s_waitcnt lgkmcnt(1)
	v_fmac_f32_e32 v7, v178, v38
	s_waitcnt lgkmcnt(0)
	v_fmac_f32_e32 v8, v178, v42
	v_fmac_f32_e32 v7, v179, v39
	v_fmac_f32_e32 v8, v179, v43
	v_fmac_f32_e32 v7, v180, v40
	v_fmac_f32_e32 v8, v180, v44
	s_waitcnt vmcnt(12)
	v_fmac_f32_e32 v0, v181, v27
	ds_read_b128 v[24:27], v9 offset:464
	ds_read_b128 v[28:31], v9 offset:4560
	ds_read_b128 v[32:35], v9 offset:8656
	v_fmac_f32_e32 v7, v181, v41
	v_fmac_f32_e32 v8, v181, v45
	s_waitcnt lgkmcnt(2)
	s_waitcnt vmcnt(11)
	v_fmac_f32_e32 v0, v182, v24
	s_waitcnt lgkmcnt(1)
	v_fmac_f32_e32 v7, v182, v28
	s_waitcnt lgkmcnt(0)
	v_fmac_f32_e32 v8, v182, v32
	s_waitcnt vmcnt(10)
	v_fmac_f32_e32 v0, v183, v25
	v_fmac_f32_e32 v7, v183, v29
	v_fmac_f32_e32 v8, v183, v33
	s_waitcnt vmcnt(9)
	v_fmac_f32_e32 v0, v184, v26
	v_fmac_f32_e32 v7, v184, v30
	v_fmac_f32_e32 v8, v184, v34
	s_waitcnt vmcnt(8)
	v_fmac_f32_e32 v0, v185, v27
	v_fmac_f32_e32 v7, v185, v31
	v_fmac_f32_e32 v8, v185, v35
	ds_read_b128 v[24:27], v9 offset:480
	ds_read_b128 v[28:31], v9 offset:4576
	ds_read_b128 v[32:35], v9 offset:8672
	s_waitcnt lgkmcnt(2)
	s_waitcnt vmcnt(7)
	v_fmac_f32_e32 v0, v186, v24
	s_waitcnt lgkmcnt(1)
	v_fmac_f32_e32 v7, v186, v28
	s_waitcnt lgkmcnt(0)
	v_fmac_f32_e32 v8, v186, v32
	s_waitcnt vmcnt(6)
	v_fmac_f32_e32 v0, v187, v25
	v_fmac_f32_e32 v7, v187, v29
	v_fmac_f32_e32 v8, v187, v33
	s_waitcnt vmcnt(5)
	v_fmac_f32_e32 v0, v188, v26
	v_fmac_f32_e32 v7, v188, v30
	v_fmac_f32_e32 v8, v188, v34
	ds_read_b128 v[14:17], v9 offset:496
	ds_read_b128 v[18:21], v9 offset:4592
	s_waitcnt vmcnt(4)
	v_fmac_f32_e32 v0, v189, v27
	v_fmac_f32_e32 v7, v189, v31
	v_fmac_f32_e32 v8, v189, v35
	ds_read_b128 v[22:25], v9 offset:8688
	s_waitcnt lgkmcnt(2)
	s_waitcnt vmcnt(3)
	v_fmac_f32_e32 v0, v190, v14
	s_waitcnt lgkmcnt(1)
	v_fmac_f32_e32 v7, v190, v18
	s_waitcnt vmcnt(2)
	v_fmac_f32_e32 v0, v191, v15
	v_fmac_f32_e32 v7, v191, v19
	s_waitcnt lgkmcnt(0)
	v_fmac_f32_e32 v8, v190, v22
	v_fmac_f32_e32 v8, v191, v23
	s_waitcnt vmcnt(1)
	v_fmac_f32_e32 v0, v192, v16
	v_fmac_f32_e32 v7, v192, v20
	v_fmac_f32_e32 v8, v192, v24
	s_waitcnt vmcnt(0)
	v_fmac_f32_e32 v0, v193, v17
	v_fmac_f32_e32 v7, v193, v21
	v_fmac_f32_e32 v8, v193, v25
	ds_write2st64_b32 v6, v0, v7 offset0:48 offset1:49
	ds_write_b32 v6, v8 offset:12800
	s_waitcnt lgkmcnt(0)
	s_barrier
	s_and_saveexec_b64 s[4:5], s[6:7]
	s_cbranch_execz .LBB0_1201
	s_mul_i32 s6, s8, 0x2400
	v_lshlrev_b32_e32 v0, 2, v3
	v_lshlrev_b32_e32 v6, 8, v2
	s_add_i32 s6, s6, s9
	v_add3_u32 v8, 0, v0, v6
	v_add_u32_e32 v6, s6, v3
	v_mov_b32_e32 v4, s10
	v_mov_b32_e32 v5, s11
	v_ashrrev_i32_e32 v7, 31, v6
	v_lshl_add_u64 v[4:5], v[6:7], 2, v[4:5]
	global_load_dword v3, v[4:5], off
	ds_read2st64_b32 v[4:5], v8 offset0:48 offset1:51
	s_waitcnt vmcnt(0) lgkmcnt(0)
	v_add_f32_e32 v3, v3, v4
	v_add_f32_e32 v3, v3, v5
	ds_read2st64_b32 v[4:5], v8 offset0:54 offset1:57
	s_waitcnt lgkmcnt(0)
	v_add_f32_e32 v3, v3, v4
	v_add_f32_e32 v3, v3, v5
	ds_read2st64_b32 v[4:5], v8 offset0:60 offset1:63
	s_waitcnt lgkmcnt(0)
	v_add_f32_e32 v3, v3, v4
	v_add_f32_e32 v3, v3, v5
	ds_read2st64_b32 v[4:5], v8 offset0:66 offset1:69
	s_waitcnt lgkmcnt(0)
	v_add_f32_e32 v3, v3, v4
	v_add_f32_e32 v6, v3, v5
	v_mad_u64_u32 v[2:3], s[6:7], s8, 3, v[2:3]
	v_mov_b64_e32 v[4:5], s[68:69]
	v_mad_i64_i32 v[2:3], s[6:7], v2, s87, v[4:5]
	v_lshl_add_u64 v[2:3], v[2:3], 0, s[80:81]
	v_lshl_add_u64 v[2:3], v[2:3], 0, v[0:1]
	global_store_dword v[2:3], v6, off
